# GEMM K-loops: last two LDS-DMA pieces of the 6-piece load segment issued inside that super-phase's own MFMA block (after MFMA 4 and 12); its vmcnt(8) -> vmcnt(6)
# baseline (speedup 1.0000x reference)
.LBB0_109:
	ds_read_b128 v[128:131], v168
	ds_read_b128 v[132:135], v168 offset:1024
	ds_read_b128 v[156:159], v168 offset:2048
	ds_read_b128 v[160:163], v168 offset:3072
	ds_read_b128 v[172:175], v169
	ds_read_b128 v[176:179], v169 offset:1024
	ds_read_b128 v[180:183], v169 offset:2048
	ds_read_b128 v[184:187], v169 offset:3072
	s_add_i32 s64, s25, 2
	s_add_u32 s8, s6, 0x80
	s_addc_u32 s9, s7, 0
	s_cmp_eq_u32 s96, s25
	s_cselect_b32 s9, s61, s9
	s_cselect_b32 s8, s60, s8
	s_cselect_b32 s69, s63, s11
	s_cselect_b32 s68, s62, s10
	v_lshl_add_u64 v[220:221], s[6:7], 0, v[148:149]
	s_add_i32 m0, s82, 0xc000
	ds_read_b128 v[188:191], v170
	ds_read_b128 v[192:195], v170 offset:1024
	ds_read_b128 v[196:199], v170 offset:2048
	ds_read_b128 v[200:203], v170 offset:3072
	ds_read_b128 v[204:207], v170 offset:4096
	ds_read_b128 v[208:211], v170 offset:5120
	ds_read_b128 v[212:215], v170 offset:6144
	ds_read_b128 v[216:219], v170 offset:7168
	global_load_lds_dwordx4 v[220:221], off
	v_lshl_add_u64 v[220:221], s[6:7], 0, v[150:151]
	s_add_i32 m0, s82, 0xe000
	s_nop 0
	global_load_lds_dwordx4 v[220:221], off
	s_waitcnt vmcnt(8)
	s_waitcnt lgkmcnt(0)
	s_barrier
	s_setprio 1
	s_waitcnt lgkmcnt(0)
	v_mfma_f32_16x16x32_bf16 v[124:127], v[128:131], v[188:191], v[124:127]
	v_mfma_f32_16x16x32_bf16 v[120:123], v[156:159], v[188:191], v[120:123]
	v_mfma_f32_16x16x32_bf16 v[108:111], v[128:131], v[196:199], v[108:111]
	v_mfma_f32_16x16x32_bf16 v[104:107], v[156:159], v[196:199], v[104:107]
	v_mfma_f32_16x16x32_bf16 v[92:95], v[128:131], v[204:207], v[92:95]
	v_mfma_f32_16x16x32_bf16 v[88:91], v[156:159], v[204:207], v[88:91]
	v_mfma_f32_16x16x32_bf16 v[76:79], v[128:131], v[212:215], v[76:79]
	v_mfma_f32_16x16x32_bf16 v[72:75], v[156:159], v[212:215], v[72:75]
	v_mfma_f32_16x16x32_bf16 v[124:127], v[132:135], v[192:195], v[124:127]
	v_mfma_f32_16x16x32_bf16 v[120:123], v[160:163], v[192:195], v[120:123]
	v_mfma_f32_16x16x32_bf16 v[108:111], v[132:135], v[200:203], v[108:111]
	v_mfma_f32_16x16x32_bf16 v[104:107], v[160:163], v[200:203], v[104:107]
	v_mfma_f32_16x16x32_bf16 v[92:95], v[132:135], v[208:211], v[92:95]
	v_mfma_f32_16x16x32_bf16 v[88:91], v[160:163], v[208:211], v[88:91]
	v_mfma_f32_16x16x32_bf16 v[76:79], v[132:135], v[216:219], v[76:79]
	v_mfma_f32_16x16x32_bf16 v[72:75], v[160:163], v[216:219], v[72:75]
	s_setprio 0
	s_setprio 1
	v_mfma_f32_16x16x32_bf16 v[116:119], v[172:175], v[188:191], v[116:119]
	v_mfma_f32_16x16x32_bf16 v[112:115], v[180:183], v[188:191], v[112:115]
	v_mfma_f32_16x16x32_bf16 v[100:103], v[172:175], v[196:199], v[100:103]
	v_mfma_f32_16x16x32_bf16 v[96:99], v[180:183], v[196:199], v[96:99]
	v_mfma_f32_16x16x32_bf16 v[84:87], v[172:175], v[204:207], v[84:87]
	v_mfma_f32_16x16x32_bf16 v[80:83], v[180:183], v[204:207], v[80:83]
	v_mfma_f32_16x16x32_bf16 v[68:71], v[172:175], v[212:215], v[68:71]
	v_mfma_f32_16x16x32_bf16 v[64:67], v[180:183], v[212:215], v[64:67]
	v_mfma_f32_16x16x32_bf16 v[116:119], v[176:179], v[192:195], v[116:119]
	v_mfma_f32_16x16x32_bf16 v[112:115], v[184:187], v[192:195], v[112:115]
	v_mfma_f32_16x16x32_bf16 v[100:103], v[176:179], v[200:203], v[100:103]
	v_mfma_f32_16x16x32_bf16 v[96:99], v[184:187], v[200:203], v[96:99]
	v_mfma_f32_16x16x32_bf16 v[84:87], v[176:179], v[208:211], v[84:87]
	v_mfma_f32_16x16x32_bf16 v[80:83], v[184:187], v[208:211], v[80:83]
	v_mfma_f32_16x16x32_bf16 v[68:71], v[176:179], v[216:219], v[68:71]
	v_mfma_f32_16x16x32_bf16 v[64:67], v[184:187], v[216:219], v[64:67]
	s_setprio 0
	s_barrier
	s_add_i32 s25, s97, s79
	v_lshl_add_u64 v[220:221], s[68:69], 0, v[138:139]
	s_mov_b32 m0, s25
	ds_read_b128 v[188:191], v170 offset:16384
	ds_read_b128 v[192:195], v170 offset:17408
	ds_read_b128 v[196:199], v170 offset:18432
	ds_read_b128 v[200:203], v170 offset:19456
	ds_read_b128 v[204:207], v170 offset:20480
	ds_read_b128 v[208:211], v170 offset:21504
	ds_read_b128 v[212:215], v170 offset:22528
	ds_read_b128 v[216:219], v170 offset:23552
	global_load_lds_dwordx4 v[220:221], off
	s_add_i32 m0, s25, 0x2000
	v_lshl_add_u64 v[222:223], s[68:69], 0, v[142:143]
	s_add_u32 s68, s68, s22
	s_addc_u32 s69, s69, s23
	s_add_i32 s25, s28, s79
	global_load_lds_dwordx4 v[222:223], off
	v_lshl_add_u64 v[224:225], s[68:69], 0, v[138:139]
	s_mov_b32 m0, s25
	v_lshl_add_u64 v[226:227], s[68:69], 0, v[142:143]
	global_load_lds_dwordx4 v[224:225], off
	s_add_i32 m0, s25, 0x2000
	v_lshl_add_u64 v[228:229], s[8:9], 0, v[136:137]
	global_load_lds_dwordx4 v[226:227], off
	s_waitcnt vmcnt(6)
	s_waitcnt lgkmcnt(0)
	s_barrier
	s_setprio 1
	s_waitcnt lgkmcnt(0)
	v_mfma_f32_16x16x32_bf16 v[60:63], v[128:131], v[188:191], v[60:63]
	v_mfma_f32_16x16x32_bf16 v[56:59], v[156:159], v[188:191], v[56:59]
	v_mfma_f32_16x16x32_bf16 v[44:47], v[128:131], v[196:199], v[44:47]
	v_mfma_f32_16x16x32_bf16 v[40:43], v[156:159], v[196:199], v[40:43]
	s_mov_b32 m0, s82
	v_lshl_add_u64 v[230:231], s[8:9], 0, v[140:141]
	global_load_lds_dwordx4 v[228:229], off
	v_mfma_f32_16x16x32_bf16 v[28:31], v[128:131], v[204:207], v[28:31]
	v_mfma_f32_16x16x32_bf16 v[24:27], v[156:159], v[204:207], v[24:27]
	v_mfma_f32_16x16x32_bf16 v[12:15], v[128:131], v[212:215], v[12:15]
	v_mfma_f32_16x16x32_bf16 v[8:11], v[156:159], v[212:215], v[8:11]
	v_mfma_f32_16x16x32_bf16 v[60:63], v[132:135], v[192:195], v[60:63]
	v_mfma_f32_16x16x32_bf16 v[56:59], v[160:163], v[192:195], v[56:59]
	v_mfma_f32_16x16x32_bf16 v[44:47], v[132:135], v[200:203], v[44:47]
	v_mfma_f32_16x16x32_bf16 v[40:43], v[160:163], v[200:203], v[40:43]
	s_mov_b32 m0, s83
	s_nop 0
	global_load_lds_dwordx4 v[230:231], off
	v_mfma_f32_16x16x32_bf16 v[28:31], v[132:135], v[208:211], v[28:31]
	v_mfma_f32_16x16x32_bf16 v[24:27], v[160:163], v[208:211], v[24:27]
	v_mfma_f32_16x16x32_bf16 v[12:15], v[132:135], v[216:219], v[12:15]
	v_mfma_f32_16x16x32_bf16 v[8:11], v[160:163], v[216:219], v[8:11]
	s_setprio 0
	s_setprio 1
	v_mfma_f32_16x16x32_bf16 v[52:55], v[172:175], v[188:191], v[52:55]
	v_mfma_f32_16x16x32_bf16 v[48:51], v[180:183], v[188:191], v[48:51]
	v_mfma_f32_16x16x32_bf16 v[36:39], v[172:175], v[196:199], v[36:39]
	v_mfma_f32_16x16x32_bf16 v[32:35], v[180:183], v[196:199], v[32:35]
	v_mfma_f32_16x16x32_bf16 v[20:23], v[172:175], v[204:207], v[20:23]
	v_mfma_f32_16x16x32_bf16 v[16:19], v[180:183], v[204:207], v[16:19]
	v_mfma_f32_16x16x32_bf16 v[4:7], v[172:175], v[212:215], v[4:7]
	v_mfma_f32_16x16x32_bf16 v[0:3], v[180:183], v[212:215], v[0:3]
	v_mfma_f32_16x16x32_bf16 v[52:55], v[176:179], v[192:195], v[52:55]
	v_mfma_f32_16x16x32_bf16 v[48:51], v[184:187], v[192:195], v[48:51]
	v_mfma_f32_16x16x32_bf16 v[36:39], v[176:179], v[200:203], v[36:39]
	v_mfma_f32_16x16x32_bf16 v[32:35], v[184:187], v[200:203], v[32:35]
	v_mfma_f32_16x16x32_bf16 v[20:23], v[176:179], v[208:211], v[20:23]
	v_mfma_f32_16x16x32_bf16 v[16:19], v[184:187], v[208:211], v[16:19]
	v_mfma_f32_16x16x32_bf16 v[4:7], v[176:179], v[216:219], v[4:7]
	v_mfma_f32_16x16x32_bf16 v[0:3], v[184:187], v[216:219], v[0:3]
	s_setprio 0
	s_barrier
	s_add_i32 s25, 0, 0x18000
	v_add_u32_e32 v144, s25, v165
	s_add_i32 s65, 0, 0x1c000
	ds_read_b128 v[128:131], v144
	ds_read_b128 v[132:135], v144 offset:1024
	ds_read_b128 v[156:159], v144 offset:2048
	ds_read_b128 v[160:163], v144 offset:3072
	v_add_u32_e32 v144, s65, v165
	ds_read_b128 v[172:175], v144
	ds_read_b128 v[176:179], v144 offset:1024
	ds_read_b128 v[180:183], v144 offset:2048
	ds_read_b128 v[184:187], v144 offset:3072
	s_add_u32 s8, s8, s22
	s_addc_u32 s9, s9, s23
	s_mov_b32 m0, s84
	v_lshl_add_u64 v[232:233], s[8:9], 0, v[136:137]
	ds_read_b128 v[188:191], v170 offset:32768
	ds_read_b128 v[192:195], v170 offset:33792
	ds_read_b128 v[196:199], v170 offset:34816
	ds_read_b128 v[200:203], v170 offset:35840
	ds_read_b128 v[204:207], v170 offset:36864
	ds_read_b128 v[208:211], v170 offset:37888
	ds_read_b128 v[212:215], v170 offset:38912
	ds_read_b128 v[216:219], v170 offset:39936
	global_load_lds_dwordx4 v[232:233], off
	v_lshl_add_u64 v[232:233], s[8:9], 0, v[140:141]
	s_mov_b32 m0, s85
	s_nop 0
	global_load_lds_dwordx4 v[232:233], off
	s_waitcnt vmcnt(8)
	s_waitcnt lgkmcnt(0)
	s_barrier
	s_setprio 1
	s_waitcnt lgkmcnt(0)
	v_mfma_f32_16x16x32_bf16 v[124:127], v[128:131], v[188:191], v[124:127]
	v_mfma_f32_16x16x32_bf16 v[120:123], v[156:159], v[188:191], v[120:123]
	v_mfma_f32_16x16x32_bf16 v[108:111], v[128:131], v[196:199], v[108:111]
	v_mfma_f32_16x16x32_bf16 v[104:107], v[156:159], v[196:199], v[104:107]
	v_mfma_f32_16x16x32_bf16 v[92:95], v[128:131], v[204:207], v[92:95]
	v_mfma_f32_16x16x32_bf16 v[88:91], v[156:159], v[204:207], v[88:91]
	v_mfma_f32_16x16x32_bf16 v[76:79], v[128:131], v[212:215], v[76:79]
	v_mfma_f32_16x16x32_bf16 v[72:75], v[156:159], v[212:215], v[72:75]
	v_mfma_f32_16x16x32_bf16 v[124:127], v[132:135], v[192:195], v[124:127]
	v_mfma_f32_16x16x32_bf16 v[120:123], v[160:163], v[192:195], v[120:123]
	v_mfma_f32_16x16x32_bf16 v[108:111], v[132:135], v[200:203], v[108:111]
	v_mfma_f32_16x16x32_bf16 v[104:107], v[160:163], v[200:203], v[104:107]
	v_mfma_f32_16x16x32_bf16 v[92:95], v[132:135], v[208:211], v[92:95]
	v_mfma_f32_16x16x32_bf16 v[88:91], v[160:163], v[208:211], v[88:91]
	v_mfma_f32_16x16x32_bf16 v[76:79], v[132:135], v[216:219], v[76:79]
	v_mfma_f32_16x16x32_bf16 v[72:75], v[160:163], v[216:219], v[72:75]
	s_setprio 0
	s_setprio 1
	v_mfma_f32_16x16x32_bf16 v[116:119], v[172:175], v[188:191], v[116:119]
	v_mfma_f32_16x16x32_bf16 v[112:115], v[180:183], v[188:191], v[112:115]
	v_mfma_f32_16x16x32_bf16 v[100:103], v[172:175], v[196:199], v[100:103]
	v_mfma_f32_16x16x32_bf16 v[96:99], v[180:183], v[196:199], v[96:99]
	v_mfma_f32_16x16x32_bf16 v[84:87], v[172:175], v[204:207], v[84:87]
	v_mfma_f32_16x16x32_bf16 v[80:83], v[180:183], v[204:207], v[80:83]
	v_mfma_f32_16x16x32_bf16 v[68:71], v[172:175], v[212:215], v[68:71]
	v_mfma_f32_16x16x32_bf16 v[64:67], v[180:183], v[212:215], v[64:67]
	v_mfma_f32_16x16x32_bf16 v[116:119], v[176:179], v[192:195], v[116:119]
	v_mfma_f32_16x16x32_bf16 v[112:115], v[184:187], v[192:195], v[112:115]
	v_mfma_f32_16x16x32_bf16 v[100:103], v[176:179], v[200:203], v[100:103]
	v_mfma_f32_16x16x32_bf16 v[96:99], v[184:187], v[200:203], v[96:99]
	v_mfma_f32_16x16x32_bf16 v[84:87], v[176:179], v[208:211], v[84:87]
	v_mfma_f32_16x16x32_bf16 v[80:83], v[184:187], v[208:211], v[80:83]
	v_mfma_f32_16x16x32_bf16 v[68:71], v[176:179], v[216:219], v[68:71]
	v_mfma_f32_16x16x32_bf16 v[64:67], v[184:187], v[216:219], v[64:67]
	s_setprio 0
	s_barrier
	s_add_i32 s8, s25, s79
	v_lshl_add_u64 v[220:221], v[220:221], 0, s[46:47]
	s_mov_b32 m0, s8
	ds_read_b128 v[188:191], v170 offset:49152
	ds_read_b128 v[192:195], v170 offset:50176
	ds_read_b128 v[196:199], v170 offset:51200
	ds_read_b128 v[200:203], v170 offset:52224
	ds_read_b128 v[204:207], v170 offset:53248
	ds_read_b128 v[208:211], v170 offset:54272
	ds_read_b128 v[212:215], v170 offset:55296
	ds_read_b128 v[216:219], v170 offset:56320
	global_load_lds_dwordx4 v[220:221], off
	v_lshl_add_u64 v[220:221], v[222:223], 0, s[46:47]
	s_add_i32 m0, s8, 0x2000
	s_add_i32 s8, s65, s79
	global_load_lds_dwordx4 v[220:221], off
	v_lshl_add_u64 v[220:221], v[224:225], 0, s[46:47]
	s_mov_b32 m0, s8
	s_nop 0
	global_load_lds_dwordx4 v[220:221], off
	v_lshl_add_u64 v[220:221], v[226:227], 0, s[46:47]
	s_add_i32 m0, s8, 0x2000
	s_nop 0
	global_load_lds_dwordx4 v[220:221], off
	s_waitcnt vmcnt(6)
	s_waitcnt lgkmcnt(0)
	s_barrier
	s_setprio 1
	s_waitcnt lgkmcnt(0)
	v_mfma_f32_16x16x32_bf16 v[60:63], v[128:131], v[188:191], v[60:63]
	v_mfma_f32_16x16x32_bf16 v[56:59], v[156:159], v[188:191], v[56:59]
	v_mfma_f32_16x16x32_bf16 v[44:47], v[128:131], v[196:199], v[44:47]
	v_mfma_f32_16x16x32_bf16 v[40:43], v[156:159], v[196:199], v[40:43]
	v_lshl_add_u64 v[220:221], v[228:229], 0, s[46:47]
	s_mov_b32 m0, s92
	s_nop 0
	global_load_lds_dwordx4 v[220:221], off
	v_mfma_f32_16x16x32_bf16 v[28:31], v[128:131], v[204:207], v[28:31]
	v_mfma_f32_16x16x32_bf16 v[24:27], v[156:159], v[204:207], v[24:27]
	v_mfma_f32_16x16x32_bf16 v[12:15], v[128:131], v[212:215], v[12:15]
	v_mfma_f32_16x16x32_bf16 v[8:11], v[156:159], v[212:215], v[8:11]
	v_mfma_f32_16x16x32_bf16 v[60:63], v[132:135], v[192:195], v[60:63]
	v_mfma_f32_16x16x32_bf16 v[56:59], v[160:163], v[192:195], v[56:59]
	v_mfma_f32_16x16x32_bf16 v[44:47], v[132:135], v[200:203], v[44:47]
	v_mfma_f32_16x16x32_bf16 v[40:43], v[160:163], v[200:203], v[40:43]
	v_lshl_add_u64 v[220:221], v[230:231], 0, s[46:47]
	s_mov_b32 m0, s93
	s_nop 0
	global_load_lds_dwordx4 v[220:221], off
	v_mfma_f32_16x16x32_bf16 v[28:31], v[132:135], v[208:211], v[28:31]
	v_mfma_f32_16x16x32_bf16 v[24:27], v[160:163], v[208:211], v[24:27]
	v_mfma_f32_16x16x32_bf16 v[12:15], v[132:135], v[216:219], v[12:15]
	v_mfma_f32_16x16x32_bf16 v[8:11], v[160:163], v[216:219], v[8:11]
	s_setprio 0
	s_setprio 1
	v_mfma_f32_16x16x32_bf16 v[52:55], v[172:175], v[188:191], v[52:55]
	v_mfma_f32_16x16x32_bf16 v[48:51], v[180:183], v[188:191], v[48:51]
	v_mfma_f32_16x16x32_bf16 v[36:39], v[172:175], v[196:199], v[36:39]
	v_mfma_f32_16x16x32_bf16 v[32:35], v[180:183], v[196:199], v[32:35]
	v_mfma_f32_16x16x32_bf16 v[20:23], v[172:175], v[204:207], v[20:23]
	v_mfma_f32_16x16x32_bf16 v[16:19], v[180:183], v[204:207], v[16:19]
	v_mfma_f32_16x16x32_bf16 v[4:7], v[172:175], v[212:215], v[4:7]
	v_mfma_f32_16x16x32_bf16 v[0:3], v[180:183], v[212:215], v[0:3]
	v_mfma_f32_16x16x32_bf16 v[52:55], v[176:179], v[192:195], v[52:55]
	v_mfma_f32_16x16x32_bf16 v[48:51], v[184:187], v[192:195], v[48:51]
	v_mfma_f32_16x16x32_bf16 v[36:39], v[176:179], v[200:203], v[36:39]
	v_mfma_f32_16x16x32_bf16 v[32:35], v[184:187], v[200:203], v[32:35]
	v_mfma_f32_16x16x32_bf16 v[20:23], v[176:179], v[208:211], v[20:23]
	v_mfma_f32_16x16x32_bf16 v[16:19], v[184:187], v[208:211], v[16:19]
	v_mfma_f32_16x16x32_bf16 v[4:7], v[176:179], v[216:219], v[4:7]
	v_mfma_f32_16x16x32_bf16 v[0:3], v[184:187], v[216:219], v[0:3]
	s_setprio 0
	s_barrier
	s_add_u32 s6, s6, 0x100
	s_addc_u32 s7, s7, 0
	s_add_u32 s10, s10, 0x100
	s_addc_u32 s11, s11, 0
	s_cmp_ge_i32 s64, s94
	s_mov_b32 s25, s64
	s_cbranch_scc0 .LBB0_109
	s_and_b64 vcc, exec, s[50:51]
	s_cbranch_vccz .LBB0_112

.LBB0_350:
	ds_read_b128 v[150:153], v147
	ds_read_b128 v[154:157], v147 offset:1024
	ds_read_b128 v[158:161], v147 offset:2048
	ds_read_b128 v[162:165], v147 offset:3072
	ds_read_b128 v[166:169], v148
	ds_read_b128 v[170:173], v148 offset:1024
	ds_read_b128 v[174:177], v148 offset:2048
	ds_read_b128 v[178:181], v148 offset:3072
	s_add_i32 s69, s54, 2
	s_add_u32 s70, s52, 0x80
	s_addc_u32 s55, s53, 0
	s_cmp_eq_u32 s57, s54
	s_cselect_b32 s54, s6, s70
	s_cselect_b32 s55, s7, s55
	s_cselect_b32 s71, s51, s68
	s_cselect_b32 s70, s50, s67
	v_lshl_add_u64 v[214:215], s[52:53], 0, v[136:137]
	s_add_i32 m0, s26, 0xc000
	ds_read_b128 v[182:185], v149
	ds_read_b128 v[186:189], v149 offset:1024
	ds_read_b128 v[190:193], v149 offset:2048
	ds_read_b128 v[194:197], v149 offset:3072
	ds_read_b128 v[198:201], v149 offset:4096
	ds_read_b128 v[202:205], v149 offset:5120
	ds_read_b128 v[206:209], v149 offset:6144
	ds_read_b128 v[210:213], v149 offset:7168
	global_load_lds_dwordx4 v[214:215], off
	v_lshl_add_u64 v[214:215], s[52:53], 0, v[138:139]
	s_add_i32 m0, s26, 0xe000
	s_nop 0
	global_load_lds_dwordx4 v[214:215], off
	s_waitcnt vmcnt(8)
	s_waitcnt lgkmcnt(0)
	s_barrier
	s_setprio 1
	s_waitcnt lgkmcnt(0)
	v_mfma_f32_16x16x32_bf16 v[120:123], v[150:153], v[182:185], v[120:123]
	v_mfma_f32_16x16x32_bf16 v[124:127], v[158:161], v[182:185], v[124:127]
	v_mfma_f32_16x16x32_bf16 v[108:111], v[150:153], v[190:193], v[108:111]
	v_mfma_f32_16x16x32_bf16 v[104:107], v[158:161], v[190:193], v[104:107]
	v_mfma_f32_16x16x32_bf16 v[92:95], v[150:153], v[198:201], v[92:95]
	v_mfma_f32_16x16x32_bf16 v[88:91], v[158:161], v[198:201], v[88:91]
	v_mfma_f32_16x16x32_bf16 v[76:79], v[150:153], v[206:209], v[76:79]
	v_mfma_f32_16x16x32_bf16 v[72:75], v[158:161], v[206:209], v[72:75]
	v_mfma_f32_16x16x32_bf16 v[120:123], v[154:157], v[186:189], v[120:123]
	v_mfma_f32_16x16x32_bf16 v[124:127], v[162:165], v[186:189], v[124:127]
	v_mfma_f32_16x16x32_bf16 v[108:111], v[154:157], v[194:197], v[108:111]
	v_mfma_f32_16x16x32_bf16 v[104:107], v[162:165], v[194:197], v[104:107]
	v_mfma_f32_16x16x32_bf16 v[92:95], v[154:157], v[202:205], v[92:95]
	v_mfma_f32_16x16x32_bf16 v[88:91], v[162:165], v[202:205], v[88:91]
	v_mfma_f32_16x16x32_bf16 v[76:79], v[154:157], v[210:213], v[76:79]
	v_mfma_f32_16x16x32_bf16 v[72:75], v[162:165], v[210:213], v[72:75]
	s_setprio 0
	s_setprio 1
	v_mfma_f32_16x16x32_bf16 v[116:119], v[166:169], v[182:185], v[116:119]
	v_mfma_f32_16x16x32_bf16 v[112:115], v[174:177], v[182:185], v[112:115]
	v_mfma_f32_16x16x32_bf16 v[100:103], v[166:169], v[190:193], v[100:103]
	v_mfma_f32_16x16x32_bf16 v[96:99], v[174:177], v[190:193], v[96:99]
	v_mfma_f32_16x16x32_bf16 v[84:87], v[166:169], v[198:201], v[84:87]
	v_mfma_f32_16x16x32_bf16 v[80:83], v[174:177], v[198:201], v[80:83]
	v_mfma_f32_16x16x32_bf16 v[68:71], v[166:169], v[206:209], v[68:71]
	v_mfma_f32_16x16x32_bf16 v[64:67], v[174:177], v[206:209], v[64:67]
	v_mfma_f32_16x16x32_bf16 v[116:119], v[170:173], v[186:189], v[116:119]
	v_mfma_f32_16x16x32_bf16 v[112:115], v[178:181], v[186:189], v[112:115]
	v_mfma_f32_16x16x32_bf16 v[100:103], v[170:173], v[194:197], v[100:103]
	v_mfma_f32_16x16x32_bf16 v[96:99], v[178:181], v[194:197], v[96:99]
	v_mfma_f32_16x16x32_bf16 v[84:87], v[170:173], v[202:205], v[84:87]
	v_mfma_f32_16x16x32_bf16 v[80:83], v[178:181], v[202:205], v[80:83]
	v_mfma_f32_16x16x32_bf16 v[68:71], v[170:173], v[210:213], v[68:71]
	v_mfma_f32_16x16x32_bf16 v[64:67], v[178:181], v[210:213], v[64:67]
	s_setprio 0
	s_barrier
	s_add_i32 s72, s58, s25
	v_lshl_add_u64 v[214:215], s[70:71], 0, v[132:133]
	s_mov_b32 m0, s72
	ds_read_b128 v[182:185], v149 offset:16384
	ds_read_b128 v[186:189], v149 offset:17408
	ds_read_b128 v[190:193], v149 offset:18432
	ds_read_b128 v[194:197], v149 offset:19456
	ds_read_b128 v[198:201], v149 offset:20480
	ds_read_b128 v[202:205], v149 offset:21504
	ds_read_b128 v[206:209], v149 offset:22528
	ds_read_b128 v[210:213], v149 offset:23552
	global_load_lds_dwordx4 v[214:215], off
	s_add_i32 m0, s72, 0x2000
	v_lshl_add_u64 v[216:217], s[70:71], 0, v[128:129]
	s_add_u32 s70, s70, s8
	s_addc_u32 s71, s71, s9
	s_add_i32 s72, s59, s25
	global_load_lds_dwordx4 v[216:217], off
	v_lshl_add_u64 v[218:219], s[70:71], 0, v[132:133]
	s_mov_b32 m0, s72
	v_lshl_add_u64 v[220:221], s[70:71], 0, v[128:129]
	global_load_lds_dwordx4 v[218:219], off
	s_add_i32 m0, s72, 0x2000
	v_lshl_add_u64 v[222:223], s[54:55], 0, v[134:135]
	global_load_lds_dwordx4 v[220:221], off
	s_waitcnt vmcnt(6)
	s_waitcnt lgkmcnt(0)
	s_barrier
	s_setprio 1
	s_waitcnt lgkmcnt(0)
	v_mfma_f32_16x16x32_bf16 v[60:63], v[150:153], v[182:185], v[60:63]
	v_mfma_f32_16x16x32_bf16 v[56:59], v[158:161], v[182:185], v[56:59]
	v_mfma_f32_16x16x32_bf16 v[44:47], v[150:153], v[190:193], v[44:47]
	v_mfma_f32_16x16x32_bf16 v[40:43], v[158:161], v[190:193], v[40:43]
	s_mov_b32 m0, s26
	v_lshl_add_u64 v[224:225], s[54:55], 0, v[130:131]
	global_load_lds_dwordx4 v[222:223], off
	v_mfma_f32_16x16x32_bf16 v[28:31], v[150:153], v[198:201], v[28:31]
	v_mfma_f32_16x16x32_bf16 v[24:27], v[158:161], v[198:201], v[24:27]
	v_mfma_f32_16x16x32_bf16 v[12:15], v[150:153], v[206:209], v[12:15]
	v_mfma_f32_16x16x32_bf16 v[8:11], v[158:161], v[206:209], v[8:11]
	v_mfma_f32_16x16x32_bf16 v[60:63], v[154:157], v[186:189], v[60:63]
	v_mfma_f32_16x16x32_bf16 v[56:59], v[162:165], v[186:189], v[56:59]
	v_mfma_f32_16x16x32_bf16 v[44:47], v[154:157], v[194:197], v[44:47]
	v_mfma_f32_16x16x32_bf16 v[40:43], v[162:165], v[194:197], v[40:43]
	s_mov_b32 m0, s27
	s_nop 0
	global_load_lds_dwordx4 v[224:225], off
	v_mfma_f32_16x16x32_bf16 v[28:31], v[154:157], v[202:205], v[28:31]
	v_mfma_f32_16x16x32_bf16 v[24:27], v[162:165], v[202:205], v[24:27]
	v_mfma_f32_16x16x32_bf16 v[12:15], v[154:157], v[210:213], v[12:15]
	v_mfma_f32_16x16x32_bf16 v[8:11], v[162:165], v[210:213], v[8:11]
	s_setprio 0
	s_setprio 1
	v_mfma_f32_16x16x32_bf16 v[52:55], v[166:169], v[182:185], v[52:55]
	v_mfma_f32_16x16x32_bf16 v[48:51], v[174:177], v[182:185], v[48:51]
	v_mfma_f32_16x16x32_bf16 v[36:39], v[166:169], v[190:193], v[36:39]
	v_mfma_f32_16x16x32_bf16 v[32:35], v[174:177], v[190:193], v[32:35]
	v_mfma_f32_16x16x32_bf16 v[20:23], v[166:169], v[198:201], v[20:23]
	v_mfma_f32_16x16x32_bf16 v[16:19], v[174:177], v[198:201], v[16:19]
	v_mfma_f32_16x16x32_bf16 v[4:7], v[166:169], v[206:209], v[4:7]
	v_mfma_f32_16x16x32_bf16 v[0:3], v[174:177], v[206:209], v[0:3]
	v_mfma_f32_16x16x32_bf16 v[52:55], v[170:173], v[186:189], v[52:55]
	v_mfma_f32_16x16x32_bf16 v[48:51], v[178:181], v[186:189], v[48:51]
	v_mfma_f32_16x16x32_bf16 v[36:39], v[170:173], v[194:197], v[36:39]
	v_mfma_f32_16x16x32_bf16 v[32:35], v[178:181], v[194:197], v[32:35]
	v_mfma_f32_16x16x32_bf16 v[20:23], v[170:173], v[202:205], v[20:23]
	v_mfma_f32_16x16x32_bf16 v[16:19], v[178:181], v[202:205], v[16:19]
	v_mfma_f32_16x16x32_bf16 v[4:7], v[170:173], v[210:213], v[4:7]
	v_mfma_f32_16x16x32_bf16 v[0:3], v[178:181], v[210:213], v[0:3]
	s_setprio 0
	s_barrier
	s_add_i32 s70, 0, 0x18000
	s_add_i32 s71, 0, 0x1c000
	v_add_u32_e32 v162, s70, v145
	v_add_u32_e32 v178, s71, v145
	ds_read_b128 v[150:153], v162
	ds_read_b128 v[154:157], v162 offset:1024
	ds_read_b128 v[158:161], v162 offset:2048
	ds_read_b128 v[162:165], v162 offset:3072
	ds_read_b128 v[166:169], v178
	ds_read_b128 v[170:173], v178 offset:1024
	ds_read_b128 v[174:177], v178 offset:2048
	ds_read_b128 v[178:181], v178 offset:3072
	s_add_u32 s54, s54, s8
	s_addc_u32 s55, s55, s9
	s_mov_b32 m0, s28
	v_lshl_add_u64 v[226:227], s[54:55], 0, v[134:135]
	ds_read_b128 v[182:185], v149 offset:32768
	ds_read_b128 v[186:189], v149 offset:33792
	ds_read_b128 v[190:193], v149 offset:34816
	ds_read_b128 v[194:197], v149 offset:35840
	ds_read_b128 v[198:201], v149 offset:36864
	ds_read_b128 v[202:205], v149 offset:37888
	ds_read_b128 v[206:209], v149 offset:38912
	ds_read_b128 v[210:213], v149 offset:39936
	global_load_lds_dwordx4 v[226:227], off
	v_lshl_add_u64 v[226:227], s[54:55], 0, v[130:131]
	s_mov_b32 m0, s29
	s_nop 0
	global_load_lds_dwordx4 v[226:227], off
	s_waitcnt vmcnt(8)
	s_waitcnt lgkmcnt(0)
	s_barrier
	s_setprio 1
	s_waitcnt lgkmcnt(0)
	v_mfma_f32_16x16x32_bf16 v[120:123], v[150:153], v[182:185], v[120:123]
	v_mfma_f32_16x16x32_bf16 v[124:127], v[158:161], v[182:185], v[124:127]
	v_mfma_f32_16x16x32_bf16 v[108:111], v[150:153], v[190:193], v[108:111]
	v_mfma_f32_16x16x32_bf16 v[104:107], v[158:161], v[190:193], v[104:107]
	v_mfma_f32_16x16x32_bf16 v[92:95], v[150:153], v[198:201], v[92:95]
	v_mfma_f32_16x16x32_bf16 v[88:91], v[158:161], v[198:201], v[88:91]
	v_mfma_f32_16x16x32_bf16 v[76:79], v[150:153], v[206:209], v[76:79]
	v_mfma_f32_16x16x32_bf16 v[72:75], v[158:161], v[206:209], v[72:75]
	v_mfma_f32_16x16x32_bf16 v[120:123], v[154:157], v[186:189], v[120:123]
	v_mfma_f32_16x16x32_bf16 v[124:127], v[162:165], v[186:189], v[124:127]
	v_mfma_f32_16x16x32_bf16 v[108:111], v[154:157], v[194:197], v[108:111]
	v_mfma_f32_16x16x32_bf16 v[104:107], v[162:165], v[194:197], v[104:107]
	v_mfma_f32_16x16x32_bf16 v[92:95], v[154:157], v[202:205], v[92:95]
	v_mfma_f32_16x16x32_bf16 v[88:91], v[162:165], v[202:205], v[88:91]
	v_mfma_f32_16x16x32_bf16 v[76:79], v[154:157], v[210:213], v[76:79]
	v_mfma_f32_16x16x32_bf16 v[72:75], v[162:165], v[210:213], v[72:75]
	s_setprio 0
	s_setprio 1
	v_mfma_f32_16x16x32_bf16 v[116:119], v[166:169], v[182:185], v[116:119]
	v_mfma_f32_16x16x32_bf16 v[112:115], v[174:177], v[182:185], v[112:115]
	v_mfma_f32_16x16x32_bf16 v[100:103], v[166:169], v[190:193], v[100:103]
	v_mfma_f32_16x16x32_bf16 v[96:99], v[174:177], v[190:193], v[96:99]
	v_mfma_f32_16x16x32_bf16 v[84:87], v[166:169], v[198:201], v[84:87]
	v_mfma_f32_16x16x32_bf16 v[80:83], v[174:177], v[198:201], v[80:83]
	v_mfma_f32_16x16x32_bf16 v[68:71], v[166:169], v[206:209], v[68:71]
	v_mfma_f32_16x16x32_bf16 v[64:67], v[174:177], v[206:209], v[64:67]
	v_mfma_f32_16x16x32_bf16 v[116:119], v[170:173], v[186:189], v[116:119]
	v_mfma_f32_16x16x32_bf16 v[112:115], v[178:181], v[186:189], v[112:115]
	v_mfma_f32_16x16x32_bf16 v[100:103], v[170:173], v[194:197], v[100:103]
	v_mfma_f32_16x16x32_bf16 v[96:99], v[178:181], v[194:197], v[96:99]
	v_mfma_f32_16x16x32_bf16 v[84:87], v[170:173], v[202:205], v[84:87]
	v_mfma_f32_16x16x32_bf16 v[80:83], v[178:181], v[202:205], v[80:83]
	v_mfma_f32_16x16x32_bf16 v[68:71], v[170:173], v[210:213], v[68:71]
	v_mfma_f32_16x16x32_bf16 v[64:67], v[178:181], v[210:213], v[64:67]
	s_setprio 0
	s_barrier
	s_add_i32 s54, s70, s25
	v_lshl_add_u64 v[214:215], v[214:215], 0, s[20:21]
	s_mov_b32 m0, s54
	ds_read_b128 v[182:185], v149 offset:49152
	ds_read_b128 v[186:189], v149 offset:50176
	ds_read_b128 v[190:193], v149 offset:51200
	ds_read_b128 v[194:197], v149 offset:52224
	ds_read_b128 v[198:201], v149 offset:53248
	ds_read_b128 v[202:205], v149 offset:54272
	ds_read_b128 v[206:209], v149 offset:55296
	ds_read_b128 v[210:213], v149 offset:56320
	global_load_lds_dwordx4 v[214:215], off
	v_lshl_add_u64 v[214:215], v[216:217], 0, s[20:21]
	s_add_i32 m0, s54, 0x2000
	s_add_i32 s54, s71, s25
	global_load_lds_dwordx4 v[214:215], off
	v_lshl_add_u64 v[214:215], v[218:219], 0, s[20:21]
	s_mov_b32 m0, s54
	s_nop 0
	global_load_lds_dwordx4 v[214:215], off
	v_lshl_add_u64 v[214:215], v[220:221], 0, s[20:21]
	s_add_i32 m0, s54, 0x2000
	s_nop 0
	global_load_lds_dwordx4 v[214:215], off
	s_waitcnt vmcnt(6)
	s_waitcnt lgkmcnt(0)
	s_barrier
	s_setprio 1
	s_waitcnt lgkmcnt(0)
	v_mfma_f32_16x16x32_bf16 v[60:63], v[150:153], v[182:185], v[60:63]
	v_mfma_f32_16x16x32_bf16 v[56:59], v[158:161], v[182:185], v[56:59]
	v_mfma_f32_16x16x32_bf16 v[44:47], v[150:153], v[190:193], v[44:47]
	v_mfma_f32_16x16x32_bf16 v[40:43], v[158:161], v[190:193], v[40:43]
	v_lshl_add_u64 v[214:215], v[222:223], 0, s[20:21]
	s_mov_b32 m0, s31
	s_nop 0
	global_load_lds_dwordx4 v[214:215], off
	v_mfma_f32_16x16x32_bf16 v[28:31], v[150:153], v[198:201], v[28:31]
	v_mfma_f32_16x16x32_bf16 v[24:27], v[158:161], v[198:201], v[24:27]
	v_mfma_f32_16x16x32_bf16 v[12:15], v[150:153], v[206:209], v[12:15]
	v_mfma_f32_16x16x32_bf16 v[8:11], v[158:161], v[206:209], v[8:11]
	v_mfma_f32_16x16x32_bf16 v[60:63], v[154:157], v[186:189], v[60:63]
	v_mfma_f32_16x16x32_bf16 v[56:59], v[162:165], v[186:189], v[56:59]
	v_mfma_f32_16x16x32_bf16 v[44:47], v[154:157], v[194:197], v[44:47]
	v_mfma_f32_16x16x32_bf16 v[40:43], v[162:165], v[194:197], v[40:43]
	v_lshl_add_u64 v[214:215], v[224:225], 0, s[20:21]
	s_mov_b32 m0, s35
	s_nop 0
	global_load_lds_dwordx4 v[214:215], off
	v_mfma_f32_16x16x32_bf16 v[28:31], v[154:157], v[202:205], v[28:31]
	v_mfma_f32_16x16x32_bf16 v[24:27], v[162:165], v[202:205], v[24:27]
	v_mfma_f32_16x16x32_bf16 v[12:15], v[154:157], v[210:213], v[12:15]
	v_mfma_f32_16x16x32_bf16 v[8:11], v[162:165], v[210:213], v[8:11]
	s_setprio 0
	s_setprio 1
	v_mfma_f32_16x16x32_bf16 v[52:55], v[166:169], v[182:185], v[52:55]
	v_mfma_f32_16x16x32_bf16 v[48:51], v[174:177], v[182:185], v[48:51]
	v_mfma_f32_16x16x32_bf16 v[36:39], v[166:169], v[190:193], v[36:39]
	v_mfma_f32_16x16x32_bf16 v[32:35], v[174:177], v[190:193], v[32:35]
	v_mfma_f32_16x16x32_bf16 v[20:23], v[166:169], v[198:201], v[20:23]
	v_mfma_f32_16x16x32_bf16 v[16:19], v[174:177], v[198:201], v[16:19]
	v_mfma_f32_16x16x32_bf16 v[4:7], v[166:169], v[206:209], v[4:7]
	v_mfma_f32_16x16x32_bf16 v[0:3], v[174:177], v[206:209], v[0:3]
	v_mfma_f32_16x16x32_bf16 v[52:55], v[170:173], v[186:189], v[52:55]
	v_mfma_f32_16x16x32_bf16 v[48:51], v[178:181], v[186:189], v[48:51]
	v_mfma_f32_16x16x32_bf16 v[36:39], v[170:173], v[194:197], v[36:39]
	v_mfma_f32_16x16x32_bf16 v[32:35], v[178:181], v[194:197], v[32:35]
	v_mfma_f32_16x16x32_bf16 v[20:23], v[170:173], v[202:205], v[20:23]
	v_mfma_f32_16x16x32_bf16 v[16:19], v[178:181], v[202:205], v[16:19]
	v_mfma_f32_16x16x32_bf16 v[4:7], v[170:173], v[210:213], v[4:7]
	v_mfma_f32_16x16x32_bf16 v[0:3], v[178:181], v[210:213], v[0:3]
	s_setprio 0
	s_barrier
	s_add_u32 s52, s52, 0x100
	s_addc_u32 s53, s53, 0
	s_add_u32 s67, s67, 0x100
	s_addc_u32 s68, s68, 0
	s_cmp_ge_i32 s69, s56
	s_mov_b32 s54, s69
	s_cbranch_scc0 .LBB0_350

.LBB0_679:
	v_add_u32_e32 v129, s71, v148
	ds_read_b128 v[150:153], v129
	ds_read_b128 v[154:157], v129 offset:1024
	ds_read_b128 v[158:161], v129 offset:2048
	ds_read_b128 v[162:165], v129 offset:3072
	v_add_u32_e32 v129, s72, v148
	ds_read_b128 v[166:169], v129
	ds_read_b128 v[170:173], v129 offset:1024
	ds_read_b128 v[174:177], v129 offset:2048
	ds_read_b128 v[178:181], v129 offset:3072
	s_add_i32 s83, s64, 2
	s_add_u32 s84, s62, 0x80
	s_addc_u32 s65, s63, 0
	s_cmp_eq_u32 s70, s64
	s_cselect_b32 s64, s12, s84
	s_cselect_b32 s65, s13, s65
	s_cselect_b32 s85, s61, s82
	s_cselect_b32 s84, s60, s81
	v_lshl_add_u64 v[130:131], s[62:63], 0, v[140:141]
	s_add_i32 m0, s29, 0xc000
	ds_read_b128 v[182:185], v149
	ds_read_b128 v[186:189], v149 offset:1024
	ds_read_b128 v[194:197], v149 offset:2048
	ds_read_b128 v[198:201], v149 offset:3072
	ds_read_b128 v[202:205], v149 offset:4096
	ds_read_b128 v[212:215], v149 offset:5120
	ds_read_b128 v[216:219], v149 offset:6144
	ds_read_b128 v[220:223], v149 offset:7168
	global_load_lds_dwordx4 v[130:131], off
	v_lshl_add_u64 v[130:131], s[62:63], 0, v[142:143]
	s_add_i32 m0, s29, 0xe000
	s_nop 0
	global_load_lds_dwordx4 v[130:131], off
	s_waitcnt vmcnt(8)
	s_waitcnt lgkmcnt(0)
	s_barrier
	s_setprio 1
	s_waitcnt lgkmcnt(0)
	v_mfma_f32_16x16x32_bf16 v[116:119], v[150:153], v[182:185], v[116:119]
	v_mfma_f32_16x16x32_bf16 v[112:115], v[158:161], v[182:185], v[112:115]
	v_mfma_f32_16x16x32_bf16 v[124:127], v[150:153], v[194:197], v[124:127]
	v_mfma_f32_16x16x32_bf16 v[120:123], v[158:161], v[194:197], v[120:123]
	v_mfma_f32_16x16x32_bf16 v[108:111], v[150:153], v[202:205], v[108:111]
	v_mfma_f32_16x16x32_bf16 v[104:107], v[158:161], v[202:205], v[104:107]
	v_mfma_f32_16x16x32_bf16 v[100:103], v[150:153], v[216:219], v[100:103]
	v_mfma_f32_16x16x32_bf16 v[96:99], v[158:161], v[216:219], v[96:99]
	v_mfma_f32_16x16x32_bf16 v[116:119], v[154:157], v[186:189], v[116:119]
	v_mfma_f32_16x16x32_bf16 v[112:115], v[162:165], v[186:189], v[112:115]
	v_mfma_f32_16x16x32_bf16 v[124:127], v[154:157], v[198:201], v[124:127]
	v_mfma_f32_16x16x32_bf16 v[120:123], v[162:165], v[198:201], v[120:123]
	v_mfma_f32_16x16x32_bf16 v[108:111], v[154:157], v[212:215], v[108:111]
	v_mfma_f32_16x16x32_bf16 v[104:107], v[162:165], v[212:215], v[104:107]
	v_mfma_f32_16x16x32_bf16 v[100:103], v[154:157], v[220:223], v[100:103]
	v_mfma_f32_16x16x32_bf16 v[96:99], v[162:165], v[220:223], v[96:99]
	s_setprio 0
	s_setprio 1
	v_mfma_f32_16x16x32_bf16 v[60:63], v[166:169], v[182:185], v[60:63]
	v_mfma_f32_16x16x32_bf16 v[56:59], v[174:177], v[182:185], v[56:59]
	v_mfma_f32_16x16x32_bf16 v[52:55], v[166:169], v[194:197], v[52:55]
	v_mfma_f32_16x16x32_bf16 v[48:51], v[174:177], v[194:197], v[48:51]
	v_mfma_f32_16x16x32_bf16 v[44:47], v[166:169], v[202:205], v[44:47]
	v_mfma_f32_16x16x32_bf16 v[40:43], v[174:177], v[202:205], v[40:43]
	v_mfma_f32_16x16x32_bf16 v[36:39], v[166:169], v[216:219], v[36:39]
	v_mfma_f32_16x16x32_bf16 v[32:35], v[174:177], v[216:219], v[32:35]
	v_mfma_f32_16x16x32_bf16 v[60:63], v[170:173], v[186:189], v[60:63]
	v_mfma_f32_16x16x32_bf16 v[56:59], v[178:181], v[186:189], v[56:59]
	v_mfma_f32_16x16x32_bf16 v[52:55], v[170:173], v[198:201], v[52:55]
	v_mfma_f32_16x16x32_bf16 v[48:51], v[178:181], v[198:201], v[48:51]
	v_mfma_f32_16x16x32_bf16 v[44:47], v[170:173], v[212:215], v[44:47]
	v_mfma_f32_16x16x32_bf16 v[40:43], v[178:181], v[212:215], v[40:43]
	v_mfma_f32_16x16x32_bf16 v[36:39], v[170:173], v[220:223], v[36:39]
	v_mfma_f32_16x16x32_bf16 v[32:35], v[178:181], v[220:223], v[32:35]
	s_setprio 0
	s_barrier
	s_add_i32 s86, s71, s28
	v_lshl_add_u64 v[130:131], s[84:85], 0, v[136:137]
	s_mov_b32 m0, s86
	ds_read_b128 v[182:185], v149 offset:16384
	ds_read_b128 v[186:189], v149 offset:17408
	ds_read_b128 v[194:197], v149 offset:18432
	ds_read_b128 v[198:201], v149 offset:19456
	ds_read_b128 v[202:205], v149 offset:20480
	ds_read_b128 v[212:215], v149 offset:21504
	ds_read_b128 v[216:219], v149 offset:22528
	ds_read_b128 v[220:223], v149 offset:23552
	global_load_lds_dwordx4 v[130:131], off
	s_add_i32 m0, s86, 0x2000
	v_lshl_add_u64 v[190:191], s[84:85], 0, v[132:133]
	s_add_u32 s84, s84, s16
	s_addc_u32 s85, s85, s17
	s_add_i32 s86, s72, s28
	global_load_lds_dwordx4 v[190:191], off
	v_lshl_add_u64 v[206:207], s[84:85], 0, v[136:137]
	s_mov_b32 m0, s86
	v_lshl_add_u64 v[224:225], s[84:85], 0, v[132:133]
	global_load_lds_dwordx4 v[206:207], off
	s_add_i32 m0, s86, 0x2000
	v_lshl_add_u64 v[226:227], s[64:65], 0, v[138:139]
	global_load_lds_dwordx4 v[224:225], off
	s_waitcnt vmcnt(6)
	s_waitcnt lgkmcnt(0)
	s_barrier
	s_setprio 1
	s_waitcnt lgkmcnt(0)
	v_mfma_f32_16x16x32_bf16 v[92:95], v[150:153], v[182:185], v[92:95]
	v_mfma_f32_16x16x32_bf16 v[88:91], v[158:161], v[182:185], v[88:91]
	v_mfma_f32_16x16x32_bf16 v[84:87], v[150:153], v[194:197], v[84:87]
	v_mfma_f32_16x16x32_bf16 v[80:83], v[158:161], v[194:197], v[80:83]
	s_mov_b32 m0, s29
	v_lshl_add_u64 v[228:229], s[64:65], 0, v[134:135]
	global_load_lds_dwordx4 v[226:227], off
	v_mfma_f32_16x16x32_bf16 v[76:79], v[150:153], v[202:205], v[76:79]
	v_mfma_f32_16x16x32_bf16 v[72:75], v[158:161], v[202:205], v[72:75]
	v_mfma_f32_16x16x32_bf16 v[68:71], v[150:153], v[216:219], v[68:71]
	v_mfma_f32_16x16x32_bf16 v[64:67], v[158:161], v[216:219], v[64:67]
	v_mfma_f32_16x16x32_bf16 v[92:95], v[154:157], v[186:189], v[92:95]
	v_mfma_f32_16x16x32_bf16 v[88:91], v[162:165], v[186:189], v[88:91]
	v_mfma_f32_16x16x32_bf16 v[84:87], v[154:157], v[198:201], v[84:87]
	v_mfma_f32_16x16x32_bf16 v[80:83], v[162:165], v[198:201], v[80:83]
	s_mov_b32 m0, s31
	s_nop 0
	global_load_lds_dwordx4 v[228:229], off
	v_mfma_f32_16x16x32_bf16 v[76:79], v[154:157], v[212:215], v[76:79]
	v_mfma_f32_16x16x32_bf16 v[72:75], v[162:165], v[212:215], v[72:75]
	v_mfma_f32_16x16x32_bf16 v[68:71], v[154:157], v[220:223], v[68:71]
	v_mfma_f32_16x16x32_bf16 v[64:67], v[162:165], v[220:223], v[64:67]
	s_setprio 0
	s_setprio 1
	v_mfma_f32_16x16x32_bf16 v[28:31], v[166:169], v[182:185], v[28:31]
	v_mfma_f32_16x16x32_bf16 v[24:27], v[174:177], v[182:185], v[24:27]
	v_mfma_f32_16x16x32_bf16 v[20:23], v[166:169], v[194:197], v[20:23]
	v_mfma_f32_16x16x32_bf16 v[16:19], v[174:177], v[194:197], v[16:19]
	v_mfma_f32_16x16x32_bf16 v[12:15], v[166:169], v[202:205], v[12:15]
	v_mfma_f32_16x16x32_bf16 v[8:11], v[174:177], v[202:205], v[8:11]
	v_mfma_f32_16x16x32_bf16 v[4:7], v[166:169], v[216:219], v[4:7]
	v_mfma_f32_16x16x32_bf16 v[0:3], v[174:177], v[216:219], v[0:3]
	v_mfma_f32_16x16x32_bf16 v[28:31], v[170:173], v[186:189], v[28:31]
	v_mfma_f32_16x16x32_bf16 v[24:27], v[178:181], v[186:189], v[24:27]
	v_mfma_f32_16x16x32_bf16 v[20:23], v[170:173], v[198:201], v[20:23]
	v_mfma_f32_16x16x32_bf16 v[16:19], v[178:181], v[198:201], v[16:19]
	v_mfma_f32_16x16x32_bf16 v[12:15], v[170:173], v[212:215], v[12:15]
	v_mfma_f32_16x16x32_bf16 v[8:11], v[178:181], v[212:215], v[8:11]
	v_mfma_f32_16x16x32_bf16 v[4:7], v[170:173], v[220:223], v[4:7]
	v_mfma_f32_16x16x32_bf16 v[0:3], v[178:181], v[220:223], v[0:3]
	s_setprio 0
	s_barrier
	s_add_i32 s84, 0, 0x18000
	v_add_u32_e32 v129, s84, v148
	s_add_i32 s85, 0, 0x1c000
	ds_read_b128 v[150:153], v129
	ds_read_b128 v[154:157], v129 offset:1024
	ds_read_b128 v[158:161], v129 offset:2048
	ds_read_b128 v[162:165], v129 offset:3072
	v_add_u32_e32 v129, s85, v148
	ds_read_b128 v[166:169], v129
	ds_read_b128 v[170:173], v129 offset:1024
	ds_read_b128 v[174:177], v129 offset:2048
	ds_read_b128 v[178:181], v129 offset:3072
	s_add_u32 s64, s64, s16
	s_addc_u32 s65, s65, s17
	s_mov_b32 m0, s41
	v_lshl_add_u64 v[230:231], s[64:65], 0, v[138:139]
	ds_read_b128 v[182:185], v149 offset:32768
	ds_read_b128 v[186:189], v149 offset:33792
	ds_read_b128 v[194:197], v149 offset:34816
	ds_read_b128 v[198:201], v149 offset:35840
	ds_read_b128 v[202:205], v149 offset:36864
	ds_read_b128 v[212:215], v149 offset:37888
	ds_read_b128 v[216:219], v149 offset:38912
	ds_read_b128 v[220:223], v149 offset:39936
	global_load_lds_dwordx4 v[230:231], off
	v_lshl_add_u64 v[230:231], s[64:65], 0, v[134:135]
	s_mov_b32 m0, s66
	s_nop 0
	global_load_lds_dwordx4 v[230:231], off
	s_waitcnt vmcnt(8)
	s_waitcnt lgkmcnt(0)
	s_barrier
	s_setprio 1
	s_waitcnt lgkmcnt(0)
	v_mfma_f32_16x16x32_bf16 v[116:119], v[150:153], v[182:185], v[116:119]
	v_mfma_f32_16x16x32_bf16 v[112:115], v[158:161], v[182:185], v[112:115]
	v_mfma_f32_16x16x32_bf16 v[124:127], v[150:153], v[194:197], v[124:127]
	v_mfma_f32_16x16x32_bf16 v[120:123], v[158:161], v[194:197], v[120:123]
	v_mfma_f32_16x16x32_bf16 v[108:111], v[150:153], v[202:205], v[108:111]
	v_mfma_f32_16x16x32_bf16 v[104:107], v[158:161], v[202:205], v[104:107]
	v_mfma_f32_16x16x32_bf16 v[100:103], v[150:153], v[216:219], v[100:103]
	v_mfma_f32_16x16x32_bf16 v[96:99], v[158:161], v[216:219], v[96:99]
	v_mfma_f32_16x16x32_bf16 v[116:119], v[154:157], v[186:189], v[116:119]
	v_mfma_f32_16x16x32_bf16 v[112:115], v[162:165], v[186:189], v[112:115]
	v_mfma_f32_16x16x32_bf16 v[124:127], v[154:157], v[198:201], v[124:127]
	v_mfma_f32_16x16x32_bf16 v[120:123], v[162:165], v[198:201], v[120:123]
	v_mfma_f32_16x16x32_bf16 v[108:111], v[154:157], v[212:215], v[108:111]
	v_mfma_f32_16x16x32_bf16 v[104:107], v[162:165], v[212:215], v[104:107]
	v_mfma_f32_16x16x32_bf16 v[100:103], v[154:157], v[220:223], v[100:103]
	v_mfma_f32_16x16x32_bf16 v[96:99], v[162:165], v[220:223], v[96:99]
	s_setprio 0
	s_setprio 1
	v_mfma_f32_16x16x32_bf16 v[60:63], v[166:169], v[182:185], v[60:63]
	v_mfma_f32_16x16x32_bf16 v[56:59], v[174:177], v[182:185], v[56:59]
	v_mfma_f32_16x16x32_bf16 v[52:55], v[166:169], v[194:197], v[52:55]
	v_mfma_f32_16x16x32_bf16 v[48:51], v[174:177], v[194:197], v[48:51]
	v_mfma_f32_16x16x32_bf16 v[44:47], v[166:169], v[202:205], v[44:47]
	v_mfma_f32_16x16x32_bf16 v[40:43], v[174:177], v[202:205], v[40:43]
	v_mfma_f32_16x16x32_bf16 v[36:39], v[166:169], v[216:219], v[36:39]
	v_mfma_f32_16x16x32_bf16 v[32:35], v[174:177], v[216:219], v[32:35]
	v_mfma_f32_16x16x32_bf16 v[60:63], v[170:173], v[186:189], v[60:63]
	v_mfma_f32_16x16x32_bf16 v[56:59], v[178:181], v[186:189], v[56:59]
	v_mfma_f32_16x16x32_bf16 v[52:55], v[170:173], v[198:201], v[52:55]
	v_mfma_f32_16x16x32_bf16 v[48:51], v[178:181], v[198:201], v[48:51]
	v_mfma_f32_16x16x32_bf16 v[44:47], v[170:173], v[212:215], v[44:47]
	v_mfma_f32_16x16x32_bf16 v[40:43], v[178:181], v[212:215], v[40:43]
	v_mfma_f32_16x16x32_bf16 v[36:39], v[170:173], v[220:223], v[36:39]
	v_mfma_f32_16x16x32_bf16 v[32:35], v[178:181], v[220:223], v[32:35]
	s_setprio 0
	s_barrier
	s_add_i32 s64, s84, s28
	v_lshl_add_u64 v[130:131], v[130:131], 0, s[56:57]
	s_mov_b32 m0, s64
	ds_read_b128 v[182:185], v149 offset:49152
	ds_read_b128 v[186:189], v149 offset:50176
	ds_read_b128 v[194:197], v149 offset:51200
	ds_read_b128 v[198:201], v149 offset:52224
	ds_read_b128 v[202:205], v149 offset:53248
	ds_read_b128 v[212:215], v149 offset:54272
	ds_read_b128 v[216:219], v149 offset:55296
	ds_read_b128 v[220:223], v149 offset:56320
	global_load_lds_dwordx4 v[130:131], off
	v_lshl_add_u64 v[130:131], v[190:191], 0, s[56:57]
	s_add_i32 m0, s64, 0x2000
	s_add_i32 s64, s85, s28
	global_load_lds_dwordx4 v[130:131], off
	v_lshl_add_u64 v[130:131], v[206:207], 0, s[56:57]
	s_mov_b32 m0, s64
	s_nop 0
	global_load_lds_dwordx4 v[130:131], off
	v_lshl_add_u64 v[130:131], v[224:225], 0, s[56:57]
	s_add_i32 m0, s64, 0x2000
	s_nop 0
	global_load_lds_dwordx4 v[130:131], off
	s_waitcnt vmcnt(6)
	s_waitcnt lgkmcnt(0)
	s_barrier
	s_setprio 1
	s_waitcnt lgkmcnt(0)
	v_mfma_f32_16x16x32_bf16 v[92:95], v[150:153], v[182:185], v[92:95]
	v_mfma_f32_16x16x32_bf16 v[88:91], v[158:161], v[182:185], v[88:91]
	v_mfma_f32_16x16x32_bf16 v[84:87], v[150:153], v[194:197], v[84:87]
	v_mfma_f32_16x16x32_bf16 v[80:83], v[158:161], v[194:197], v[80:83]
	v_lshl_add_u64 v[130:131], v[226:227], 0, s[56:57]
	s_mov_b32 m0, s47
	s_nop 0
	global_load_lds_dwordx4 v[130:131], off
	v_mfma_f32_16x16x32_bf16 v[76:79], v[150:153], v[202:205], v[76:79]
	v_mfma_f32_16x16x32_bf16 v[72:75], v[158:161], v[202:205], v[72:75]
	v_mfma_f32_16x16x32_bf16 v[68:71], v[150:153], v[216:219], v[68:71]
	v_mfma_f32_16x16x32_bf16 v[64:67], v[158:161], v[216:219], v[64:67]
	v_mfma_f32_16x16x32_bf16 v[92:95], v[154:157], v[186:189], v[92:95]
	v_mfma_f32_16x16x32_bf16 v[88:91], v[162:165], v[186:189], v[88:91]
	v_mfma_f32_16x16x32_bf16 v[84:87], v[154:157], v[198:201], v[84:87]
	v_mfma_f32_16x16x32_bf16 v[80:83], v[162:165], v[198:201], v[80:83]
	v_lshl_add_u64 v[130:131], v[228:229], 0, s[56:57]
	s_mov_b32 m0, s68
	s_nop 0
	global_load_lds_dwordx4 v[130:131], off
	v_mfma_f32_16x16x32_bf16 v[76:79], v[154:157], v[212:215], v[76:79]
	v_mfma_f32_16x16x32_bf16 v[72:75], v[162:165], v[212:215], v[72:75]
	v_mfma_f32_16x16x32_bf16 v[68:71], v[154:157], v[220:223], v[68:71]
	v_mfma_f32_16x16x32_bf16 v[64:67], v[162:165], v[220:223], v[64:67]
	s_setprio 0
	s_setprio 1
	v_mfma_f32_16x16x32_bf16 v[28:31], v[166:169], v[182:185], v[28:31]
	v_mfma_f32_16x16x32_bf16 v[24:27], v[174:177], v[182:185], v[24:27]
	v_mfma_f32_16x16x32_bf16 v[20:23], v[166:169], v[194:197], v[20:23]
	v_mfma_f32_16x16x32_bf16 v[16:19], v[174:177], v[194:197], v[16:19]
	v_mfma_f32_16x16x32_bf16 v[12:15], v[166:169], v[202:205], v[12:15]
	v_mfma_f32_16x16x32_bf16 v[8:11], v[174:177], v[202:205], v[8:11]
	v_mfma_f32_16x16x32_bf16 v[4:7], v[166:169], v[216:219], v[4:7]
	v_mfma_f32_16x16x32_bf16 v[0:3], v[174:177], v[216:219], v[0:3]
	v_mfma_f32_16x16x32_bf16 v[28:31], v[170:173], v[186:189], v[28:31]
	v_mfma_f32_16x16x32_bf16 v[24:27], v[178:181], v[186:189], v[24:27]
	v_mfma_f32_16x16x32_bf16 v[20:23], v[170:173], v[198:201], v[20:23]
	v_mfma_f32_16x16x32_bf16 v[16:19], v[178:181], v[198:201], v[16:19]
	v_mfma_f32_16x16x32_bf16 v[12:15], v[170:173], v[212:215], v[12:15]
	v_mfma_f32_16x16x32_bf16 v[8:11], v[178:181], v[212:215], v[8:11]
	v_mfma_f32_16x16x32_bf16 v[4:7], v[170:173], v[220:223], v[4:7]
	v_mfma_f32_16x16x32_bf16 v[0:3], v[178:181], v[220:223], v[0:3]
	s_setprio 0
	s_barrier
	s_add_u32 s62, s62, 0x100
	s_addc_u32 s63, s63, 0
	s_add_u32 s81, s81, 0x100
	s_addc_u32 s82, s82, 0
	s_cmp_ge_i32 s83, s69
	s_mov_b32 s64, s83
	s_cbranch_scc0 .LBB0_679

.LBB0_856:
	ds_read_b128 v[152:155], v149
	ds_read_b128 v[156:159], v149 offset:1024
	ds_read_b128 v[160:163], v149 offset:2048
	ds_read_b128 v[164:167], v149 offset:3072
	ds_read_b128 v[168:171], v150
	ds_read_b128 v[172:175], v150 offset:1024
	ds_read_b128 v[176:179], v150 offset:2048
	ds_read_b128 v[180:183], v150 offset:3072
	s_add_i32 s84, s62, 2
	s_add_u32 s85, s60, 0x80
	s_addc_u32 s63, s61, 0
	s_cmp_eq_u32 s65, s62
	s_cselect_b32 s62, s10, s85
	s_cselect_b32 s63, s11, s63
	s_cselect_b32 s87, s59, s83
	s_cselect_b32 s86, s58, s82
	v_lshl_add_u64 v[144:145], s[60:61], 0, v[136:137]
	s_add_i32 m0, s25, 0xc000
	ds_read_b128 v[184:187], v151
	ds_read_b128 v[188:191], v151 offset:1024
	ds_read_b128 v[192:195], v151 offset:2048
	ds_read_b128 v[196:199], v151 offset:3072
	ds_read_b128 v[200:203], v151 offset:4096
	ds_read_b128 v[204:207], v151 offset:5120
	ds_read_b128 v[208:211], v151 offset:6144
	ds_read_b128 v[212:215], v151 offset:7168
	global_load_lds_dwordx4 v[144:145], off
	v_lshl_add_u64 v[144:145], s[60:61], 0, v[138:139]
	s_add_i32 m0, s25, 0xe000
	s_nop 0
	global_load_lds_dwordx4 v[144:145], off
	s_waitcnt vmcnt(8)
	s_waitcnt lgkmcnt(0)
	s_barrier
	s_setprio 1
	s_waitcnt lgkmcnt(0)
	v_mfma_f32_16x16x32_bf16 v[120:123], v[152:155], v[184:187], v[120:123]
	v_mfma_f32_16x16x32_bf16 v[124:127], v[160:163], v[184:187], v[124:127]
	v_mfma_f32_16x16x32_bf16 v[108:111], v[152:155], v[192:195], v[108:111]
	v_mfma_f32_16x16x32_bf16 v[104:107], v[160:163], v[192:195], v[104:107]
	v_mfma_f32_16x16x32_bf16 v[92:95], v[152:155], v[200:203], v[92:95]
	v_mfma_f32_16x16x32_bf16 v[88:91], v[160:163], v[200:203], v[88:91]
	v_mfma_f32_16x16x32_bf16 v[76:79], v[152:155], v[208:211], v[76:79]
	v_mfma_f32_16x16x32_bf16 v[72:75], v[160:163], v[208:211], v[72:75]
	v_mfma_f32_16x16x32_bf16 v[120:123], v[156:159], v[188:191], v[120:123]
	v_mfma_f32_16x16x32_bf16 v[124:127], v[164:167], v[188:191], v[124:127]
	v_mfma_f32_16x16x32_bf16 v[108:111], v[156:159], v[196:199], v[108:111]
	v_mfma_f32_16x16x32_bf16 v[104:107], v[164:167], v[196:199], v[104:107]
	v_mfma_f32_16x16x32_bf16 v[92:95], v[156:159], v[204:207], v[92:95]
	v_mfma_f32_16x16x32_bf16 v[88:91], v[164:167], v[204:207], v[88:91]
	v_mfma_f32_16x16x32_bf16 v[76:79], v[156:159], v[212:215], v[76:79]
	v_mfma_f32_16x16x32_bf16 v[72:75], v[164:167], v[212:215], v[72:75]
	s_setprio 0
	s_setprio 1
	v_mfma_f32_16x16x32_bf16 v[116:119], v[168:171], v[184:187], v[116:119]
	v_mfma_f32_16x16x32_bf16 v[112:115], v[176:179], v[184:187], v[112:115]
	v_mfma_f32_16x16x32_bf16 v[100:103], v[168:171], v[192:195], v[100:103]
	v_mfma_f32_16x16x32_bf16 v[96:99], v[176:179], v[192:195], v[96:99]
	v_mfma_f32_16x16x32_bf16 v[84:87], v[168:171], v[200:203], v[84:87]
	v_mfma_f32_16x16x32_bf16 v[80:83], v[176:179], v[200:203], v[80:83]
	v_mfma_f32_16x16x32_bf16 v[68:71], v[168:171], v[208:211], v[68:71]
	v_mfma_f32_16x16x32_bf16 v[64:67], v[176:179], v[208:211], v[64:67]
	v_mfma_f32_16x16x32_bf16 v[116:119], v[172:175], v[188:191], v[116:119]
	v_mfma_f32_16x16x32_bf16 v[112:115], v[180:183], v[188:191], v[112:115]
	v_mfma_f32_16x16x32_bf16 v[100:103], v[172:175], v[196:199], v[100:103]
	v_mfma_f32_16x16x32_bf16 v[96:99], v[180:183], v[196:199], v[96:99]
	v_mfma_f32_16x16x32_bf16 v[84:87], v[172:175], v[204:207], v[84:87]
	v_mfma_f32_16x16x32_bf16 v[80:83], v[180:183], v[204:207], v[80:83]
	v_mfma_f32_16x16x32_bf16 v[68:71], v[172:175], v[212:215], v[68:71]
	v_mfma_f32_16x16x32_bf16 v[64:67], v[180:183], v[212:215], v[64:67]
	s_setprio 0
	s_barrier
	s_add_i32 s85, s67, s24
	v_lshl_add_u64 v[144:145], s[86:87], 0, v[132:133]
	s_mov_b32 m0, s85
	ds_read_b128 v[184:187], v151 offset:16384
	ds_read_b128 v[188:191], v151 offset:17408
	ds_read_b128 v[192:195], v151 offset:18432
	ds_read_b128 v[196:199], v151 offset:19456
	ds_read_b128 v[200:203], v151 offset:20480
	ds_read_b128 v[204:207], v151 offset:21504
	ds_read_b128 v[208:211], v151 offset:22528
	ds_read_b128 v[212:215], v151 offset:23552
	global_load_lds_dwordx4 v[144:145], off
	s_add_i32 m0, s85, 0x2000
	v_lshl_add_u64 v[216:217], s[86:87], 0, v[128:129]
	s_add_u32 s86, s86, s34
	s_addc_u32 s87, s87, s35
	s_add_i32 s85, s68, s24
	global_load_lds_dwordx4 v[216:217], off
	v_lshl_add_u64 v[218:219], s[86:87], 0, v[132:133]
	s_mov_b32 m0, s85
	v_lshl_add_u64 v[220:221], s[86:87], 0, v[128:129]
	global_load_lds_dwordx4 v[218:219], off
	s_add_i32 m0, s85, 0x2000
	v_lshl_add_u64 v[222:223], s[62:63], 0, v[134:135]
	global_load_lds_dwordx4 v[220:221], off
	s_waitcnt vmcnt(6)
	s_waitcnt lgkmcnt(0)
	s_barrier
	s_setprio 1
	s_waitcnt lgkmcnt(0)
	v_mfma_f32_16x16x32_bf16 v[60:63], v[152:155], v[184:187], v[60:63]
	v_mfma_f32_16x16x32_bf16 v[56:59], v[160:163], v[184:187], v[56:59]
	v_mfma_f32_16x16x32_bf16 v[44:47], v[152:155], v[192:195], v[44:47]
	v_mfma_f32_16x16x32_bf16 v[40:43], v[160:163], v[192:195], v[40:43]
	s_mov_b32 m0, s25
	v_lshl_add_u64 v[224:225], s[62:63], 0, v[130:131]
	global_load_lds_dwordx4 v[222:223], off
	v_mfma_f32_16x16x32_bf16 v[28:31], v[152:155], v[200:203], v[28:31]
	v_mfma_f32_16x16x32_bf16 v[24:27], v[160:163], v[200:203], v[24:27]
	v_mfma_f32_16x16x32_bf16 v[12:15], v[152:155], v[208:211], v[12:15]
	v_mfma_f32_16x16x32_bf16 v[8:11], v[160:163], v[208:211], v[8:11]
	v_mfma_f32_16x16x32_bf16 v[60:63], v[156:159], v[188:191], v[60:63]
	v_mfma_f32_16x16x32_bf16 v[56:59], v[164:167], v[188:191], v[56:59]
	v_mfma_f32_16x16x32_bf16 v[44:47], v[156:159], v[196:199], v[44:47]
	v_mfma_f32_16x16x32_bf16 v[40:43], v[164:167], v[196:199], v[40:43]
	s_mov_b32 m0, s26
	s_nop 0
	global_load_lds_dwordx4 v[224:225], off
	v_mfma_f32_16x16x32_bf16 v[28:31], v[156:159], v[204:207], v[28:31]
	v_mfma_f32_16x16x32_bf16 v[24:27], v[164:167], v[204:207], v[24:27]
	v_mfma_f32_16x16x32_bf16 v[12:15], v[156:159], v[212:215], v[12:15]
	v_mfma_f32_16x16x32_bf16 v[8:11], v[164:167], v[212:215], v[8:11]
	s_setprio 0
	s_setprio 1
	v_mfma_f32_16x16x32_bf16 v[52:55], v[168:171], v[184:187], v[52:55]
	v_mfma_f32_16x16x32_bf16 v[48:51], v[176:179], v[184:187], v[48:51]
	v_mfma_f32_16x16x32_bf16 v[36:39], v[168:171], v[192:195], v[36:39]
	v_mfma_f32_16x16x32_bf16 v[32:35], v[176:179], v[192:195], v[32:35]
	v_mfma_f32_16x16x32_bf16 v[20:23], v[168:171], v[200:203], v[20:23]
	v_mfma_f32_16x16x32_bf16 v[16:19], v[176:179], v[200:203], v[16:19]
	v_mfma_f32_16x16x32_bf16 v[4:7], v[168:171], v[208:211], v[4:7]
	v_mfma_f32_16x16x32_bf16 v[0:3], v[176:179], v[208:211], v[0:3]
	v_mfma_f32_16x16x32_bf16 v[52:55], v[172:175], v[188:191], v[52:55]
	v_mfma_f32_16x16x32_bf16 v[48:51], v[180:183], v[188:191], v[48:51]
	v_mfma_f32_16x16x32_bf16 v[36:39], v[172:175], v[196:199], v[36:39]
	v_mfma_f32_16x16x32_bf16 v[32:35], v[180:183], v[196:199], v[32:35]
	v_mfma_f32_16x16x32_bf16 v[20:23], v[172:175], v[204:207], v[20:23]
	v_mfma_f32_16x16x32_bf16 v[16:19], v[180:183], v[204:207], v[16:19]
	v_mfma_f32_16x16x32_bf16 v[4:7], v[172:175], v[212:215], v[4:7]
	v_mfma_f32_16x16x32_bf16 v[0:3], v[180:183], v[212:215], v[0:3]
	s_setprio 0
	s_barrier
	s_add_i32 s85, 0, 0x18000
	s_add_i32 s86, 0, 0x1c000
	v_add_u32_e32 v164, s85, v147
	v_add_u32_e32 v180, s86, v147
	ds_read_b128 v[152:155], v164
	ds_read_b128 v[156:159], v164 offset:1024
	ds_read_b128 v[160:163], v164 offset:2048
	ds_read_b128 v[164:167], v164 offset:3072
	ds_read_b128 v[168:171], v180
	ds_read_b128 v[172:175], v180 offset:1024
	ds_read_b128 v[176:179], v180 offset:2048
	ds_read_b128 v[180:183], v180 offset:3072
	s_add_u32 s62, s62, s34
	s_addc_u32 s63, s63, s35
	s_mov_b32 m0, s27
	v_lshl_add_u64 v[226:227], s[62:63], 0, v[134:135]
	ds_read_b128 v[184:187], v151 offset:32768
	ds_read_b128 v[188:191], v151 offset:33792
	ds_read_b128 v[192:195], v151 offset:34816
	ds_read_b128 v[196:199], v151 offset:35840
	ds_read_b128 v[200:203], v151 offset:36864
	ds_read_b128 v[204:207], v151 offset:37888
	ds_read_b128 v[208:211], v151 offset:38912
	ds_read_b128 v[212:215], v151 offset:39936
	global_load_lds_dwordx4 v[226:227], off
	v_lshl_add_u64 v[226:227], s[62:63], 0, v[130:131]
	s_mov_b32 m0, s28
	s_nop 0
	global_load_lds_dwordx4 v[226:227], off
	s_waitcnt vmcnt(8)
	s_waitcnt lgkmcnt(0)
	s_barrier
	s_setprio 1
	s_waitcnt lgkmcnt(0)
	v_mfma_f32_16x16x32_bf16 v[120:123], v[152:155], v[184:187], v[120:123]
	v_mfma_f32_16x16x32_bf16 v[124:127], v[160:163], v[184:187], v[124:127]
	v_mfma_f32_16x16x32_bf16 v[108:111], v[152:155], v[192:195], v[108:111]
	v_mfma_f32_16x16x32_bf16 v[104:107], v[160:163], v[192:195], v[104:107]
	v_mfma_f32_16x16x32_bf16 v[92:95], v[152:155], v[200:203], v[92:95]
	v_mfma_f32_16x16x32_bf16 v[88:91], v[160:163], v[200:203], v[88:91]
	v_mfma_f32_16x16x32_bf16 v[76:79], v[152:155], v[208:211], v[76:79]
	v_mfma_f32_16x16x32_bf16 v[72:75], v[160:163], v[208:211], v[72:75]
	v_mfma_f32_16x16x32_bf16 v[120:123], v[156:159], v[188:191], v[120:123]
	v_mfma_f32_16x16x32_bf16 v[124:127], v[164:167], v[188:191], v[124:127]
	v_mfma_f32_16x16x32_bf16 v[108:111], v[156:159], v[196:199], v[108:111]
	v_mfma_f32_16x16x32_bf16 v[104:107], v[164:167], v[196:199], v[104:107]
	v_mfma_f32_16x16x32_bf16 v[92:95], v[156:159], v[204:207], v[92:95]
	v_mfma_f32_16x16x32_bf16 v[88:91], v[164:167], v[204:207], v[88:91]
	v_mfma_f32_16x16x32_bf16 v[76:79], v[156:159], v[212:215], v[76:79]
	v_mfma_f32_16x16x32_bf16 v[72:75], v[164:167], v[212:215], v[72:75]
	s_setprio 0
	s_setprio 1
	v_mfma_f32_16x16x32_bf16 v[116:119], v[168:171], v[184:187], v[116:119]
	v_mfma_f32_16x16x32_bf16 v[112:115], v[176:179], v[184:187], v[112:115]
	v_mfma_f32_16x16x32_bf16 v[100:103], v[168:171], v[192:195], v[100:103]
	v_mfma_f32_16x16x32_bf16 v[96:99], v[176:179], v[192:195], v[96:99]
	v_mfma_f32_16x16x32_bf16 v[84:87], v[168:171], v[200:203], v[84:87]
	v_mfma_f32_16x16x32_bf16 v[80:83], v[176:179], v[200:203], v[80:83]
	v_mfma_f32_16x16x32_bf16 v[68:71], v[168:171], v[208:211], v[68:71]
	v_mfma_f32_16x16x32_bf16 v[64:67], v[176:179], v[208:211], v[64:67]
	v_mfma_f32_16x16x32_bf16 v[116:119], v[172:175], v[188:191], v[116:119]
	v_mfma_f32_16x16x32_bf16 v[112:115], v[180:183], v[188:191], v[112:115]
	v_mfma_f32_16x16x32_bf16 v[100:103], v[172:175], v[196:199], v[100:103]
	v_mfma_f32_16x16x32_bf16 v[96:99], v[180:183], v[196:199], v[96:99]
	v_mfma_f32_16x16x32_bf16 v[84:87], v[172:175], v[204:207], v[84:87]
	v_mfma_f32_16x16x32_bf16 v[80:83], v[180:183], v[204:207], v[80:83]
	v_mfma_f32_16x16x32_bf16 v[68:71], v[172:175], v[212:215], v[68:71]
	v_mfma_f32_16x16x32_bf16 v[64:67], v[180:183], v[212:215], v[64:67]
	s_setprio 0
	s_barrier
	s_add_i32 s62, s85, s24
	v_lshl_add_u64 v[144:145], v[144:145], 0, s[44:45]
	s_mov_b32 m0, s62
	ds_read_b128 v[184:187], v151 offset:49152
	ds_read_b128 v[188:191], v151 offset:50176
	ds_read_b128 v[192:195], v151 offset:51200
	ds_read_b128 v[196:199], v151 offset:52224
	ds_read_b128 v[200:203], v151 offset:53248
	ds_read_b128 v[204:207], v151 offset:54272
	ds_read_b128 v[208:211], v151 offset:55296
	ds_read_b128 v[212:215], v151 offset:56320
	global_load_lds_dwordx4 v[144:145], off
	v_lshl_add_u64 v[144:145], v[216:217], 0, s[44:45]
	s_add_i32 m0, s62, 0x2000
	s_add_i32 s62, s86, s24
	global_load_lds_dwordx4 v[144:145], off
	v_lshl_add_u64 v[144:145], v[218:219], 0, s[44:45]
	s_mov_b32 m0, s62
	s_nop 0
	global_load_lds_dwordx4 v[144:145], off
	v_lshl_add_u64 v[144:145], v[220:221], 0, s[44:45]
	s_add_i32 m0, s62, 0x2000
	s_nop 0
	global_load_lds_dwordx4 v[144:145], off
	s_waitcnt vmcnt(6)
	s_waitcnt lgkmcnt(0)
	s_barrier
	s_setprio 1
	s_waitcnt lgkmcnt(0)
	v_mfma_f32_16x16x32_bf16 v[60:63], v[152:155], v[184:187], v[60:63]
	v_mfma_f32_16x16x32_bf16 v[56:59], v[160:163], v[184:187], v[56:59]
	v_mfma_f32_16x16x32_bf16 v[44:47], v[152:155], v[192:195], v[44:47]
	v_mfma_f32_16x16x32_bf16 v[40:43], v[160:163], v[192:195], v[40:43]
	v_lshl_add_u64 v[144:145], v[222:223], 0, s[44:45]
	s_mov_b32 m0, s30
	s_nop 0
	global_load_lds_dwordx4 v[144:145], off
	v_mfma_f32_16x16x32_bf16 v[28:31], v[152:155], v[200:203], v[28:31]
	v_mfma_f32_16x16x32_bf16 v[24:27], v[160:163], v[200:203], v[24:27]
	v_mfma_f32_16x16x32_bf16 v[12:15], v[152:155], v[208:211], v[12:15]
	v_mfma_f32_16x16x32_bf16 v[8:11], v[160:163], v[208:211], v[8:11]
	v_mfma_f32_16x16x32_bf16 v[60:63], v[156:159], v[188:191], v[60:63]
	v_mfma_f32_16x16x32_bf16 v[56:59], v[164:167], v[188:191], v[56:59]
	v_mfma_f32_16x16x32_bf16 v[44:47], v[156:159], v[196:199], v[44:47]
	v_mfma_f32_16x16x32_bf16 v[40:43], v[164:167], v[196:199], v[40:43]
	v_lshl_add_u64 v[144:145], v[224:225], 0, s[44:45]
	s_mov_b32 m0, s31
	s_nop 0
	global_load_lds_dwordx4 v[144:145], off
	v_mfma_f32_16x16x32_bf16 v[28:31], v[156:159], v[204:207], v[28:31]
	v_mfma_f32_16x16x32_bf16 v[24:27], v[164:167], v[204:207], v[24:27]
	v_mfma_f32_16x16x32_bf16 v[12:15], v[156:159], v[212:215], v[12:15]
	v_mfma_f32_16x16x32_bf16 v[8:11], v[164:167], v[212:215], v[8:11]
	s_setprio 0
	s_setprio 1
	v_mfma_f32_16x16x32_bf16 v[52:55], v[168:171], v[184:187], v[52:55]
	v_mfma_f32_16x16x32_bf16 v[48:51], v[176:179], v[184:187], v[48:51]
	v_mfma_f32_16x16x32_bf16 v[36:39], v[168:171], v[192:195], v[36:39]
	v_mfma_f32_16x16x32_bf16 v[32:35], v[176:179], v[192:195], v[32:35]
	v_mfma_f32_16x16x32_bf16 v[20:23], v[168:171], v[200:203], v[20:23]
	v_mfma_f32_16x16x32_bf16 v[16:19], v[176:179], v[200:203], v[16:19]
	v_mfma_f32_16x16x32_bf16 v[4:7], v[168:171], v[208:211], v[4:7]
	v_mfma_f32_16x16x32_bf16 v[0:3], v[176:179], v[208:211], v[0:3]
	v_mfma_f32_16x16x32_bf16 v[52:55], v[172:175], v[188:191], v[52:55]
	v_mfma_f32_16x16x32_bf16 v[48:51], v[180:183], v[188:191], v[48:51]
	v_mfma_f32_16x16x32_bf16 v[36:39], v[172:175], v[196:199], v[36:39]
	v_mfma_f32_16x16x32_bf16 v[32:35], v[180:183], v[196:199], v[32:35]
	v_mfma_f32_16x16x32_bf16 v[20:23], v[172:175], v[204:207], v[20:23]
	v_mfma_f32_16x16x32_bf16 v[16:19], v[180:183], v[204:207], v[16:19]
	v_mfma_f32_16x16x32_bf16 v[4:7], v[172:175], v[212:215], v[4:7]
	v_mfma_f32_16x16x32_bf16 v[0:3], v[180:183], v[212:215], v[0:3]
	s_setprio 0
	s_barrier
	s_add_u32 s60, s60, 0x100
	s_addc_u32 s61, s61, 0
	s_add_u32 s82, s82, 0x100
	s_addc_u32 s83, s83, 0
	s_cmp_ge_i32 s84, s64
	s_mov_b32 s62, s84
	s_cbranch_scc0 .LBB0_856

.LBB0_960:
	v_add_u32_e32 v129, s64, v148
	ds_read_b128 v[150:153], v129
	ds_read_b128 v[154:157], v129 offset:1024
	ds_read_b128 v[158:161], v129 offset:2048
	ds_read_b128 v[162:165], v129 offset:3072
	v_add_u32_e32 v129, s65, v148
	ds_read_b128 v[166:169], v129
	ds_read_b128 v[170:173], v129 offset:1024
	ds_read_b128 v[174:177], v129 offset:2048
	ds_read_b128 v[178:181], v129 offset:3072
	s_add_i32 s76, s56, 2
	s_add_u32 s77, s54, 0x80
	s_addc_u32 s57, s55, 0
	s_cmp_eq_u32 s63, s56
	s_cselect_b32 s56, s12, s77
	s_cselect_b32 s57, s13, s57
	s_cselect_b32 s81, s53, s75
	s_cselect_b32 s80, s52, s72
	v_lshl_add_u64 v[130:131], s[54:55], 0, v[140:141]
	s_add_i32 m0, s29, 0xc000
	ds_read_b128 v[182:185], v149
	ds_read_b128 v[186:189], v149 offset:1024
	ds_read_b128 v[194:197], v149 offset:2048
	ds_read_b128 v[198:201], v149 offset:3072
	ds_read_b128 v[206:209], v149 offset:4096
	ds_read_b128 v[210:213], v149 offset:5120
	ds_read_b128 v[214:217], v149 offset:6144
	ds_read_b128 v[218:221], v149 offset:7168
	global_load_lds_dwordx4 v[130:131], off
	v_lshl_add_u64 v[130:131], s[54:55], 0, v[142:143]
	s_add_i32 m0, s29, 0xe000
	s_nop 0
	global_load_lds_dwordx4 v[130:131], off
	s_waitcnt vmcnt(8)
	s_waitcnt lgkmcnt(0)
	s_barrier
	s_setprio 1
	s_waitcnt lgkmcnt(0)
	v_mfma_f32_16x16x32_bf16 v[124:127], v[150:153], v[182:185], v[124:127]
	v_mfma_f32_16x16x32_bf16 v[120:123], v[158:161], v[182:185], v[120:123]
	v_mfma_f32_16x16x32_bf16 v[116:119], v[150:153], v[194:197], v[116:119]
	v_mfma_f32_16x16x32_bf16 v[112:115], v[158:161], v[194:197], v[112:115]
	v_mfma_f32_16x16x32_bf16 v[108:111], v[150:153], v[206:209], v[108:111]
	v_mfma_f32_16x16x32_bf16 v[104:107], v[158:161], v[206:209], v[104:107]
	v_mfma_f32_16x16x32_bf16 v[100:103], v[150:153], v[214:217], v[100:103]
	v_mfma_f32_16x16x32_bf16 v[96:99], v[158:161], v[214:217], v[96:99]
	v_mfma_f32_16x16x32_bf16 v[124:127], v[154:157], v[186:189], v[124:127]
	v_mfma_f32_16x16x32_bf16 v[120:123], v[162:165], v[186:189], v[120:123]
	v_mfma_f32_16x16x32_bf16 v[116:119], v[154:157], v[198:201], v[116:119]
	v_mfma_f32_16x16x32_bf16 v[112:115], v[162:165], v[198:201], v[112:115]
	v_mfma_f32_16x16x32_bf16 v[108:111], v[154:157], v[210:213], v[108:111]
	v_mfma_f32_16x16x32_bf16 v[104:107], v[162:165], v[210:213], v[104:107]
	v_mfma_f32_16x16x32_bf16 v[100:103], v[154:157], v[218:221], v[100:103]
	v_mfma_f32_16x16x32_bf16 v[96:99], v[162:165], v[218:221], v[96:99]
	s_setprio 0
	s_setprio 1
	v_mfma_f32_16x16x32_bf16 v[60:63], v[166:169], v[182:185], v[60:63]
	v_mfma_f32_16x16x32_bf16 v[56:59], v[174:177], v[182:185], v[56:59]
	v_mfma_f32_16x16x32_bf16 v[52:55], v[166:169], v[194:197], v[52:55]
	v_mfma_f32_16x16x32_bf16 v[48:51], v[174:177], v[194:197], v[48:51]
	v_mfma_f32_16x16x32_bf16 v[44:47], v[166:169], v[206:209], v[44:47]
	v_mfma_f32_16x16x32_bf16 v[40:43], v[174:177], v[206:209], v[40:43]
	v_mfma_f32_16x16x32_bf16 v[36:39], v[166:169], v[214:217], v[36:39]
	v_mfma_f32_16x16x32_bf16 v[32:35], v[174:177], v[214:217], v[32:35]
	v_mfma_f32_16x16x32_bf16 v[60:63], v[170:173], v[186:189], v[60:63]
	v_mfma_f32_16x16x32_bf16 v[56:59], v[178:181], v[186:189], v[56:59]
	v_mfma_f32_16x16x32_bf16 v[52:55], v[170:173], v[198:201], v[52:55]
	v_mfma_f32_16x16x32_bf16 v[48:51], v[178:181], v[198:201], v[48:51]
	v_mfma_f32_16x16x32_bf16 v[44:47], v[170:173], v[210:213], v[44:47]
	v_mfma_f32_16x16x32_bf16 v[40:43], v[178:181], v[210:213], v[40:43]
	v_mfma_f32_16x16x32_bf16 v[36:39], v[170:173], v[218:221], v[36:39]
	v_mfma_f32_16x16x32_bf16 v[32:35], v[178:181], v[218:221], v[32:35]
	s_setprio 0
	s_barrier
	s_add_i32 s77, s64, s26
	v_lshl_add_u64 v[130:131], s[80:81], 0, v[136:137]
	s_mov_b32 m0, s77
	ds_read_b128 v[182:185], v149 offset:16384
	ds_read_b128 v[186:189], v149 offset:17408
	ds_read_b128 v[194:197], v149 offset:18432
	ds_read_b128 v[198:201], v149 offset:19456
	ds_read_b128 v[206:209], v149 offset:20480
	ds_read_b128 v[210:213], v149 offset:21504
	ds_read_b128 v[214:217], v149 offset:22528
	ds_read_b128 v[218:221], v149 offset:23552
	global_load_lds_dwordx4 v[130:131], off
	s_add_i32 m0, s77, 0x2000
	v_lshl_add_u64 v[190:191], s[80:81], 0, v[132:133]
	s_add_u32 s80, s80, s40
	s_addc_u32 s81, s81, s41
	s_add_i32 s77, s65, s26
	global_load_lds_dwordx4 v[190:191], off
	v_lshl_add_u64 v[202:203], s[80:81], 0, v[136:137]
	s_mov_b32 m0, s77
	v_lshl_add_u64 v[222:223], s[80:81], 0, v[132:133]
	global_load_lds_dwordx4 v[202:203], off
	s_add_i32 m0, s77, 0x2000
	v_lshl_add_u64 v[224:225], s[56:57], 0, v[138:139]
	global_load_lds_dwordx4 v[222:223], off
	s_waitcnt vmcnt(6)
	s_waitcnt lgkmcnt(0)
	s_barrier
	s_setprio 1
	s_waitcnt lgkmcnt(0)
	v_mfma_f32_16x16x32_bf16 v[92:95], v[150:153], v[182:185], v[92:95]
	v_mfma_f32_16x16x32_bf16 v[88:91], v[158:161], v[182:185], v[88:91]
	v_mfma_f32_16x16x32_bf16 v[84:87], v[150:153], v[194:197], v[84:87]
	v_mfma_f32_16x16x32_bf16 v[80:83], v[158:161], v[194:197], v[80:83]
	s_mov_b32 m0, s29
	v_lshl_add_u64 v[226:227], s[56:57], 0, v[134:135]
	global_load_lds_dwordx4 v[224:225], off
	v_mfma_f32_16x16x32_bf16 v[76:79], v[150:153], v[206:209], v[76:79]
	v_mfma_f32_16x16x32_bf16 v[72:75], v[158:161], v[206:209], v[72:75]
	v_mfma_f32_16x16x32_bf16 v[68:71], v[150:153], v[214:217], v[68:71]
	v_mfma_f32_16x16x32_bf16 v[64:67], v[158:161], v[214:217], v[64:67]
	v_mfma_f32_16x16x32_bf16 v[92:95], v[154:157], v[186:189], v[92:95]
	v_mfma_f32_16x16x32_bf16 v[88:91], v[162:165], v[186:189], v[88:91]
	v_mfma_f32_16x16x32_bf16 v[84:87], v[154:157], v[198:201], v[84:87]
	v_mfma_f32_16x16x32_bf16 v[80:83], v[162:165], v[198:201], v[80:83]
	s_mov_b32 m0, s31
	s_nop 0
	global_load_lds_dwordx4 v[226:227], off
	v_mfma_f32_16x16x32_bf16 v[76:79], v[154:157], v[210:213], v[76:79]
	v_mfma_f32_16x16x32_bf16 v[72:75], v[162:165], v[210:213], v[72:75]
	v_mfma_f32_16x16x32_bf16 v[68:71], v[154:157], v[218:221], v[68:71]
	v_mfma_f32_16x16x32_bf16 v[64:67], v[162:165], v[218:221], v[64:67]
	s_setprio 0
	s_setprio 1
	v_mfma_f32_16x16x32_bf16 v[28:31], v[166:169], v[182:185], v[28:31]
	v_mfma_f32_16x16x32_bf16 v[24:27], v[174:177], v[182:185], v[24:27]
	v_mfma_f32_16x16x32_bf16 v[20:23], v[166:169], v[194:197], v[20:23]
	v_mfma_f32_16x16x32_bf16 v[16:19], v[174:177], v[194:197], v[16:19]
	v_mfma_f32_16x16x32_bf16 v[12:15], v[166:169], v[206:209], v[12:15]
	v_mfma_f32_16x16x32_bf16 v[8:11], v[174:177], v[206:209], v[8:11]
	v_mfma_f32_16x16x32_bf16 v[4:7], v[166:169], v[214:217], v[4:7]
	v_mfma_f32_16x16x32_bf16 v[0:3], v[174:177], v[214:217], v[0:3]
	v_mfma_f32_16x16x32_bf16 v[28:31], v[170:173], v[186:189], v[28:31]
	v_mfma_f32_16x16x32_bf16 v[24:27], v[178:181], v[186:189], v[24:27]
	v_mfma_f32_16x16x32_bf16 v[20:23], v[170:173], v[198:201], v[20:23]
	v_mfma_f32_16x16x32_bf16 v[16:19], v[178:181], v[198:201], v[16:19]
	v_mfma_f32_16x16x32_bf16 v[12:15], v[170:173], v[210:213], v[12:15]
	v_mfma_f32_16x16x32_bf16 v[8:11], v[178:181], v[210:213], v[8:11]
	v_mfma_f32_16x16x32_bf16 v[4:7], v[170:173], v[218:221], v[4:7]
	v_mfma_f32_16x16x32_bf16 v[0:3], v[178:181], v[218:221], v[0:3]
	s_setprio 0
	s_barrier
	s_add_i32 s77, 0, 0x18000
	v_add_u32_e32 v129, s77, v148
	s_add_i32 s80, 0, 0x1c000
	ds_read_b128 v[150:153], v129
	ds_read_b128 v[154:157], v129 offset:1024
	ds_read_b128 v[158:161], v129 offset:2048
	ds_read_b128 v[162:165], v129 offset:3072
	v_add_u32_e32 v129, s80, v148
	ds_read_b128 v[166:169], v129
	ds_read_b128 v[170:173], v129 offset:1024
	ds_read_b128 v[174:177], v129 offset:2048
	ds_read_b128 v[178:181], v129 offset:3072
	s_add_u32 s56, s56, s40
	s_addc_u32 s57, s57, s41
	s_mov_b32 m0, s39
	v_lshl_add_u64 v[228:229], s[56:57], 0, v[138:139]
	ds_read_b128 v[182:185], v149 offset:32768
	ds_read_b128 v[186:189], v149 offset:33792
	ds_read_b128 v[194:197], v149 offset:34816
	ds_read_b128 v[198:201], v149 offset:35840
	ds_read_b128 v[206:209], v149 offset:36864
	ds_read_b128 v[210:213], v149 offset:37888
	ds_read_b128 v[214:217], v149 offset:38912
	ds_read_b128 v[218:221], v149 offset:39936
	global_load_lds_dwordx4 v[228:229], off
	v_lshl_add_u64 v[228:229], s[56:57], 0, v[134:135]
	s_mov_b32 m0, s58
	s_nop 0
	global_load_lds_dwordx4 v[228:229], off
	s_waitcnt vmcnt(8)
	s_waitcnt lgkmcnt(0)
	s_barrier
	s_setprio 1
	s_waitcnt lgkmcnt(0)
	v_mfma_f32_16x16x32_bf16 v[124:127], v[150:153], v[182:185], v[124:127]
	v_mfma_f32_16x16x32_bf16 v[120:123], v[158:161], v[182:185], v[120:123]
	v_mfma_f32_16x16x32_bf16 v[116:119], v[150:153], v[194:197], v[116:119]
	v_mfma_f32_16x16x32_bf16 v[112:115], v[158:161], v[194:197], v[112:115]
	v_mfma_f32_16x16x32_bf16 v[108:111], v[150:153], v[206:209], v[108:111]
	v_mfma_f32_16x16x32_bf16 v[104:107], v[158:161], v[206:209], v[104:107]
	v_mfma_f32_16x16x32_bf16 v[100:103], v[150:153], v[214:217], v[100:103]
	v_mfma_f32_16x16x32_bf16 v[96:99], v[158:161], v[214:217], v[96:99]
	v_mfma_f32_16x16x32_bf16 v[124:127], v[154:157], v[186:189], v[124:127]
	v_mfma_f32_16x16x32_bf16 v[120:123], v[162:165], v[186:189], v[120:123]
	v_mfma_f32_16x16x32_bf16 v[116:119], v[154:157], v[198:201], v[116:119]
	v_mfma_f32_16x16x32_bf16 v[112:115], v[162:165], v[198:201], v[112:115]
	v_mfma_f32_16x16x32_bf16 v[108:111], v[154:157], v[210:213], v[108:111]
	v_mfma_f32_16x16x32_bf16 v[104:107], v[162:165], v[210:213], v[104:107]
	v_mfma_f32_16x16x32_bf16 v[100:103], v[154:157], v[218:221], v[100:103]
	v_mfma_f32_16x16x32_bf16 v[96:99], v[162:165], v[218:221], v[96:99]
	s_setprio 0
	s_setprio 1
	v_mfma_f32_16x16x32_bf16 v[60:63], v[166:169], v[182:185], v[60:63]
	v_mfma_f32_16x16x32_bf16 v[56:59], v[174:177], v[182:185], v[56:59]
	v_mfma_f32_16x16x32_bf16 v[52:55], v[166:169], v[194:197], v[52:55]
	v_mfma_f32_16x16x32_bf16 v[48:51], v[174:177], v[194:197], v[48:51]
	v_mfma_f32_16x16x32_bf16 v[44:47], v[166:169], v[206:209], v[44:47]
	v_mfma_f32_16x16x32_bf16 v[40:43], v[174:177], v[206:209], v[40:43]
	v_mfma_f32_16x16x32_bf16 v[36:39], v[166:169], v[214:217], v[36:39]
	v_mfma_f32_16x16x32_bf16 v[32:35], v[174:177], v[214:217], v[32:35]
	v_mfma_f32_16x16x32_bf16 v[60:63], v[170:173], v[186:189], v[60:63]
	v_mfma_f32_16x16x32_bf16 v[56:59], v[178:181], v[186:189], v[56:59]
	v_mfma_f32_16x16x32_bf16 v[52:55], v[170:173], v[198:201], v[52:55]
	v_mfma_f32_16x16x32_bf16 v[48:51], v[178:181], v[198:201], v[48:51]
	v_mfma_f32_16x16x32_bf16 v[44:47], v[170:173], v[210:213], v[44:47]
	v_mfma_f32_16x16x32_bf16 v[40:43], v[178:181], v[210:213], v[40:43]
	v_mfma_f32_16x16x32_bf16 v[36:39], v[170:173], v[218:221], v[36:39]
	v_mfma_f32_16x16x32_bf16 v[32:35], v[178:181], v[218:221], v[32:35]
	s_setprio 0
	s_barrier
	s_add_i32 s56, s77, s26
	v_lshl_add_u64 v[130:131], v[130:131], 0, s[48:49]
	s_mov_b32 m0, s56
	ds_read_b128 v[182:185], v149 offset:49152
	ds_read_b128 v[186:189], v149 offset:50176
	ds_read_b128 v[194:197], v149 offset:51200
	ds_read_b128 v[198:201], v149 offset:52224
	ds_read_b128 v[206:209], v149 offset:53248
	ds_read_b128 v[210:213], v149 offset:54272
	ds_read_b128 v[214:217], v149 offset:55296
	ds_read_b128 v[218:221], v149 offset:56320
	global_load_lds_dwordx4 v[130:131], off
	v_lshl_add_u64 v[130:131], v[190:191], 0, s[48:49]
	s_add_i32 m0, s56, 0x2000
	s_add_i32 s56, s80, s26
	global_load_lds_dwordx4 v[130:131], off
	v_lshl_add_u64 v[130:131], v[202:203], 0, s[48:49]
	s_mov_b32 m0, s56
	s_nop 0
	global_load_lds_dwordx4 v[130:131], off
	v_lshl_add_u64 v[130:131], v[222:223], 0, s[48:49]
	s_add_i32 m0, s56, 0x2000
	s_nop 0
	global_load_lds_dwordx4 v[130:131], off
	s_waitcnt vmcnt(6)
	s_waitcnt lgkmcnt(0)
	s_barrier
	s_setprio 1
	s_waitcnt lgkmcnt(0)
	v_mfma_f32_16x16x32_bf16 v[92:95], v[150:153], v[182:185], v[92:95]
	v_mfma_f32_16x16x32_bf16 v[88:91], v[158:161], v[182:185], v[88:91]
	v_mfma_f32_16x16x32_bf16 v[84:87], v[150:153], v[194:197], v[84:87]
	v_mfma_f32_16x16x32_bf16 v[80:83], v[158:161], v[194:197], v[80:83]
	v_lshl_add_u64 v[130:131], v[224:225], 0, s[48:49]
	s_mov_b32 m0, s59
	s_nop 0
	global_load_lds_dwordx4 v[130:131], off
	v_mfma_f32_16x16x32_bf16 v[76:79], v[150:153], v[206:209], v[76:79]
	v_mfma_f32_16x16x32_bf16 v[72:75], v[158:161], v[206:209], v[72:75]
	v_mfma_f32_16x16x32_bf16 v[68:71], v[150:153], v[214:217], v[68:71]
	v_mfma_f32_16x16x32_bf16 v[64:67], v[158:161], v[214:217], v[64:67]
	v_mfma_f32_16x16x32_bf16 v[92:95], v[154:157], v[186:189], v[92:95]
	v_mfma_f32_16x16x32_bf16 v[88:91], v[162:165], v[186:189], v[88:91]
	v_mfma_f32_16x16x32_bf16 v[84:87], v[154:157], v[198:201], v[84:87]
	v_mfma_f32_16x16x32_bf16 v[80:83], v[162:165], v[198:201], v[80:83]
	v_lshl_add_u64 v[130:131], v[226:227], 0, s[48:49]
	s_mov_b32 m0, s61
	s_nop 0
	global_load_lds_dwordx4 v[130:131], off
	v_mfma_f32_16x16x32_bf16 v[76:79], v[154:157], v[210:213], v[76:79]
	v_mfma_f32_16x16x32_bf16 v[72:75], v[162:165], v[210:213], v[72:75]
	v_mfma_f32_16x16x32_bf16 v[68:71], v[154:157], v[218:221], v[68:71]
	v_mfma_f32_16x16x32_bf16 v[64:67], v[162:165], v[218:221], v[64:67]
	s_setprio 0
	s_setprio 1
	v_mfma_f32_16x16x32_bf16 v[28:31], v[166:169], v[182:185], v[28:31]
	v_mfma_f32_16x16x32_bf16 v[24:27], v[174:177], v[182:185], v[24:27]
	v_mfma_f32_16x16x32_bf16 v[20:23], v[166:169], v[194:197], v[20:23]
	v_mfma_f32_16x16x32_bf16 v[16:19], v[174:177], v[194:197], v[16:19]
	v_mfma_f32_16x16x32_bf16 v[12:15], v[166:169], v[206:209], v[12:15]
	v_mfma_f32_16x16x32_bf16 v[8:11], v[174:177], v[206:209], v[8:11]
	v_mfma_f32_16x16x32_bf16 v[4:7], v[166:169], v[214:217], v[4:7]
	v_mfma_f32_16x16x32_bf16 v[0:3], v[174:177], v[214:217], v[0:3]
	v_mfma_f32_16x16x32_bf16 v[28:31], v[170:173], v[186:189], v[28:31]
	v_mfma_f32_16x16x32_bf16 v[24:27], v[178:181], v[186:189], v[24:27]
	v_mfma_f32_16x16x32_bf16 v[20:23], v[170:173], v[198:201], v[20:23]
	v_mfma_f32_16x16x32_bf16 v[16:19], v[178:181], v[198:201], v[16:19]
	v_mfma_f32_16x16x32_bf16 v[12:15], v[170:173], v[210:213], v[12:15]
	v_mfma_f32_16x16x32_bf16 v[8:11], v[178:181], v[210:213], v[8:11]
	v_mfma_f32_16x16x32_bf16 v[4:7], v[170:173], v[218:221], v[4:7]
	v_mfma_f32_16x16x32_bf16 v[0:3], v[178:181], v[218:221], v[0:3]
	s_setprio 0
	s_barrier
	s_add_u32 s54, s54, 0x100
	s_addc_u32 s55, s55, 0
	s_add_u32 s72, s72, 0x100
	s_addc_u32 s75, s75, 0
	s_cmp_ge_i32 s76, s62
	s_mov_b32 s56, s76
	s_cbranch_scc0 .LBB0_960

.LBB0_1086:
	ds_read_b128 v[128:131], v195
	ds_read_b128 v[132:135], v195 offset:1024
	ds_read_b128 v[136:139], v195 offset:2048
	ds_read_b128 v[140:143], v195 offset:3072
	ds_read_b128 v[144:147], v196
	ds_read_b128 v[148:151], v196 offset:1024
	ds_read_b128 v[152:155], v196 offset:2048
	ds_read_b128 v[156:159], v196 offset:3072
	s_add_i32 s59, s40, 2
	s_add_u32 s60, s38, 0x80
	s_addc_u32 s41, s39, 0
	s_cmp_eq_u32 s50, s40
	s_cselect_b32 s40, s4, s60
	s_cselect_b32 s41, s5, s41
	s_cselect_b32 s61, s37, s58
	s_cselect_b32 s60, s36, s57
	v_lshl_add_u64 v[214:215], s[38:39], 0, v[176:177]
	s_add_i32 m0, s42, 0xc000
	ds_read_b128 v[160:163], v197
	ds_read_b128 v[164:167], v197 offset:1024
	ds_read_b128 v[184:187], v197 offset:2048
	ds_read_b128 v[188:191], v197 offset:3072
	ds_read_b128 v[198:201], v197 offset:4096
	ds_read_b128 v[202:205], v197 offset:5120
	ds_read_b128 v[206:209], v197 offset:6144
	ds_read_b128 v[210:213], v197 offset:7168
	global_load_lds_dwordx4 v[214:215], off
	v_lshl_add_u64 v[214:215], s[38:39], 0, v[178:179]
	s_add_i32 m0, s42, 0xe000
	s_nop 0
	global_load_lds_dwordx4 v[214:215], off
	s_waitcnt vmcnt(8)
	s_waitcnt lgkmcnt(0)
	s_barrier
	s_setprio 1
	s_waitcnt lgkmcnt(0)
	v_mfma_f32_16x16x32_bf16 v[124:127], v[128:131], v[160:163], v[124:127]
	v_mfma_f32_16x16x32_bf16 v[120:123], v[136:139], v[160:163], v[120:123]
	v_mfma_f32_16x16x32_bf16 v[108:111], v[128:131], v[184:187], v[108:111]
	v_mfma_f32_16x16x32_bf16 v[104:107], v[136:139], v[184:187], v[104:107]
	v_mfma_f32_16x16x32_bf16 v[92:95], v[128:131], v[198:201], v[92:95]
	v_mfma_f32_16x16x32_bf16 v[88:91], v[136:139], v[198:201], v[88:91]
	v_mfma_f32_16x16x32_bf16 v[76:79], v[128:131], v[206:209], v[76:79]
	v_mfma_f32_16x16x32_bf16 v[72:75], v[136:139], v[206:209], v[72:75]
	v_mfma_f32_16x16x32_bf16 v[124:127], v[132:135], v[164:167], v[124:127]
	v_mfma_f32_16x16x32_bf16 v[120:123], v[140:143], v[164:167], v[120:123]
	v_mfma_f32_16x16x32_bf16 v[108:111], v[132:135], v[188:191], v[108:111]
	v_mfma_f32_16x16x32_bf16 v[104:107], v[140:143], v[188:191], v[104:107]
	v_mfma_f32_16x16x32_bf16 v[92:95], v[132:135], v[202:205], v[92:95]
	v_mfma_f32_16x16x32_bf16 v[88:91], v[140:143], v[202:205], v[88:91]
	v_mfma_f32_16x16x32_bf16 v[76:79], v[132:135], v[210:213], v[76:79]
	v_mfma_f32_16x16x32_bf16 v[72:75], v[140:143], v[210:213], v[72:75]
	s_setprio 0
	s_setprio 1
	v_mfma_f32_16x16x32_bf16 v[116:119], v[144:147], v[160:163], v[116:119]
	v_mfma_f32_16x16x32_bf16 v[112:115], v[152:155], v[160:163], v[112:115]
	v_mfma_f32_16x16x32_bf16 v[100:103], v[144:147], v[184:187], v[100:103]
	v_mfma_f32_16x16x32_bf16 v[96:99], v[152:155], v[184:187], v[96:99]
	v_mfma_f32_16x16x32_bf16 v[84:87], v[144:147], v[198:201], v[84:87]
	v_mfma_f32_16x16x32_bf16 v[80:83], v[152:155], v[198:201], v[80:83]
	v_mfma_f32_16x16x32_bf16 v[68:71], v[144:147], v[206:209], v[68:71]
	v_mfma_f32_16x16x32_bf16 v[64:67], v[152:155], v[206:209], v[64:67]
	v_mfma_f32_16x16x32_bf16 v[116:119], v[148:151], v[164:167], v[116:119]
	v_mfma_f32_16x16x32_bf16 v[112:115], v[156:159], v[164:167], v[112:115]
	v_mfma_f32_16x16x32_bf16 v[100:103], v[148:151], v[188:191], v[100:103]
	v_mfma_f32_16x16x32_bf16 v[96:99], v[156:159], v[188:191], v[96:99]
	v_mfma_f32_16x16x32_bf16 v[84:87], v[148:151], v[202:205], v[84:87]
	v_mfma_f32_16x16x32_bf16 v[80:83], v[156:159], v[202:205], v[80:83]
	v_mfma_f32_16x16x32_bf16 v[68:71], v[148:151], v[210:213], v[68:71]
	v_mfma_f32_16x16x32_bf16 v[64:67], v[156:159], v[210:213], v[64:67]
	s_setprio 0
	s_barrier
	s_add_i32 s62, s51, s15
	v_lshl_add_u64 v[214:215], s[60:61], 0, v[172:173]
	s_mov_b32 m0, s62
	ds_read_b128 v[160:163], v197 offset:16384
	ds_read_b128 v[164:167], v197 offset:17408
	ds_read_b128 v[184:187], v197 offset:18432
	ds_read_b128 v[188:191], v197 offset:19456
	ds_read_b128 v[198:201], v197 offset:20480
	ds_read_b128 v[202:205], v197 offset:21504
	ds_read_b128 v[206:209], v197 offset:22528
	ds_read_b128 v[210:213], v197 offset:23552
	global_load_lds_dwordx4 v[214:215], off
	s_add_i32 m0, s62, 0x2000
	v_lshl_add_u64 v[216:217], s[60:61], 0, v[168:169]
	s_add_u32 s60, s60, s18
	s_addc_u32 s61, s61, s19
	s_add_i32 s62, s52, s15
	global_load_lds_dwordx4 v[216:217], off
	v_lshl_add_u64 v[218:219], s[60:61], 0, v[172:173]
	s_mov_b32 m0, s62
	v_lshl_add_u64 v[220:221], s[60:61], 0, v[168:169]
	global_load_lds_dwordx4 v[218:219], off
	s_add_i32 m0, s62, 0x2000
	v_lshl_add_u64 v[222:223], s[40:41], 0, v[174:175]
	global_load_lds_dwordx4 v[220:221], off
	s_waitcnt vmcnt(6)
	s_waitcnt lgkmcnt(0)
	s_barrier
	s_setprio 1
	s_waitcnt lgkmcnt(0)
	v_mfma_f32_16x16x32_bf16 v[60:63], v[128:131], v[160:163], v[60:63]
	v_mfma_f32_16x16x32_bf16 v[56:59], v[136:139], v[160:163], v[56:59]
	v_mfma_f32_16x16x32_bf16 v[44:47], v[128:131], v[184:187], v[44:47]
	v_mfma_f32_16x16x32_bf16 v[40:43], v[136:139], v[184:187], v[40:43]
	s_mov_b32 m0, s42
	v_lshl_add_u64 v[224:225], s[40:41], 0, v[170:171]
	global_load_lds_dwordx4 v[222:223], off
	v_mfma_f32_16x16x32_bf16 v[28:31], v[128:131], v[198:201], v[28:31]
	v_mfma_f32_16x16x32_bf16 v[24:27], v[136:139], v[198:201], v[24:27]
	v_mfma_f32_16x16x32_bf16 v[12:15], v[128:131], v[206:209], v[12:15]
	v_mfma_f32_16x16x32_bf16 v[8:11], v[136:139], v[206:209], v[8:11]
	v_mfma_f32_16x16x32_bf16 v[60:63], v[132:135], v[164:167], v[60:63]
	v_mfma_f32_16x16x32_bf16 v[56:59], v[140:143], v[164:167], v[56:59]
	v_mfma_f32_16x16x32_bf16 v[44:47], v[132:135], v[188:191], v[44:47]
	v_mfma_f32_16x16x32_bf16 v[40:43], v[140:143], v[188:191], v[40:43]
	s_mov_b32 m0, s43
	s_nop 0
	global_load_lds_dwordx4 v[224:225], off
	v_mfma_f32_16x16x32_bf16 v[28:31], v[132:135], v[202:205], v[28:31]
	v_mfma_f32_16x16x32_bf16 v[24:27], v[140:143], v[202:205], v[24:27]
	v_mfma_f32_16x16x32_bf16 v[12:15], v[132:135], v[210:213], v[12:15]
	v_mfma_f32_16x16x32_bf16 v[8:11], v[140:143], v[210:213], v[8:11]
	s_setprio 0
	s_setprio 1
	v_mfma_f32_16x16x32_bf16 v[52:55], v[144:147], v[160:163], v[52:55]
	v_mfma_f32_16x16x32_bf16 v[48:51], v[152:155], v[160:163], v[48:51]
	v_mfma_f32_16x16x32_bf16 v[36:39], v[144:147], v[184:187], v[36:39]
	v_mfma_f32_16x16x32_bf16 v[32:35], v[152:155], v[184:187], v[32:35]
	v_mfma_f32_16x16x32_bf16 v[20:23], v[144:147], v[198:201], v[20:23]
	v_mfma_f32_16x16x32_bf16 v[16:19], v[152:155], v[198:201], v[16:19]
	v_mfma_f32_16x16x32_bf16 v[4:7], v[144:147], v[206:209], v[4:7]
	v_mfma_f32_16x16x32_bf16 v[0:3], v[152:155], v[206:209], v[0:3]
	v_mfma_f32_16x16x32_bf16 v[52:55], v[148:151], v[164:167], v[52:55]
	v_mfma_f32_16x16x32_bf16 v[48:51], v[156:159], v[164:167], v[48:51]
	v_mfma_f32_16x16x32_bf16 v[36:39], v[148:151], v[188:191], v[36:39]
	v_mfma_f32_16x16x32_bf16 v[32:35], v[156:159], v[188:191], v[32:35]
	v_mfma_f32_16x16x32_bf16 v[20:23], v[148:151], v[202:205], v[20:23]
	v_mfma_f32_16x16x32_bf16 v[16:19], v[156:159], v[202:205], v[16:19]
	v_mfma_f32_16x16x32_bf16 v[4:7], v[148:151], v[210:213], v[4:7]
	v_mfma_f32_16x16x32_bf16 v[0:3], v[156:159], v[210:213], v[0:3]
	s_setprio 0
	s_barrier
	s_add_i32 s60, 0, 0x18000
	s_add_i32 s61, 0, 0x1c000
	v_add_u32_e32 v140, s60, v193
	v_add_u32_e32 v156, s61, v193
	ds_read_b128 v[128:131], v140
	ds_read_b128 v[132:135], v140 offset:1024
	ds_read_b128 v[136:139], v140 offset:2048
	ds_read_b128 v[140:143], v140 offset:3072
	ds_read_b128 v[144:147], v156
	ds_read_b128 v[148:151], v156 offset:1024
	ds_read_b128 v[152:155], v156 offset:2048
	ds_read_b128 v[156:159], v156 offset:3072
	s_add_u32 s40, s40, s18
	s_addc_u32 s41, s41, s19
	s_mov_b32 m0, s44
	v_lshl_add_u64 v[226:227], s[40:41], 0, v[174:175]
	ds_read_b128 v[160:163], v197 offset:32768
	ds_read_b128 v[164:167], v197 offset:33792
	ds_read_b128 v[184:187], v197 offset:34816
	ds_read_b128 v[188:191], v197 offset:35840
	ds_read_b128 v[198:201], v197 offset:36864
	ds_read_b128 v[202:205], v197 offset:37888
	ds_read_b128 v[206:209], v197 offset:38912
	ds_read_b128 v[210:213], v197 offset:39936
	global_load_lds_dwordx4 v[226:227], off
	v_lshl_add_u64 v[226:227], s[40:41], 0, v[170:171]
	s_mov_b32 m0, s45
	s_nop 0
	global_load_lds_dwordx4 v[226:227], off
	s_waitcnt vmcnt(8)
	s_waitcnt lgkmcnt(0)
	s_barrier
	s_setprio 1
	s_waitcnt lgkmcnt(0)
	v_mfma_f32_16x16x32_bf16 v[124:127], v[128:131], v[160:163], v[124:127]
	v_mfma_f32_16x16x32_bf16 v[120:123], v[136:139], v[160:163], v[120:123]
	v_mfma_f32_16x16x32_bf16 v[108:111], v[128:131], v[184:187], v[108:111]
	v_mfma_f32_16x16x32_bf16 v[104:107], v[136:139], v[184:187], v[104:107]
	v_mfma_f32_16x16x32_bf16 v[92:95], v[128:131], v[198:201], v[92:95]
	v_mfma_f32_16x16x32_bf16 v[88:91], v[136:139], v[198:201], v[88:91]
	v_mfma_f32_16x16x32_bf16 v[76:79], v[128:131], v[206:209], v[76:79]
	v_mfma_f32_16x16x32_bf16 v[72:75], v[136:139], v[206:209], v[72:75]
	v_mfma_f32_16x16x32_bf16 v[124:127], v[132:135], v[164:167], v[124:127]
	v_mfma_f32_16x16x32_bf16 v[120:123], v[140:143], v[164:167], v[120:123]
	v_mfma_f32_16x16x32_bf16 v[108:111], v[132:135], v[188:191], v[108:111]
	v_mfma_f32_16x16x32_bf16 v[104:107], v[140:143], v[188:191], v[104:107]
	v_mfma_f32_16x16x32_bf16 v[92:95], v[132:135], v[202:205], v[92:95]
	v_mfma_f32_16x16x32_bf16 v[88:91], v[140:143], v[202:205], v[88:91]
	v_mfma_f32_16x16x32_bf16 v[76:79], v[132:135], v[210:213], v[76:79]
	v_mfma_f32_16x16x32_bf16 v[72:75], v[140:143], v[210:213], v[72:75]
	s_setprio 0
	s_setprio 1
	v_mfma_f32_16x16x32_bf16 v[116:119], v[144:147], v[160:163], v[116:119]
	v_mfma_f32_16x16x32_bf16 v[112:115], v[152:155], v[160:163], v[112:115]
	v_mfma_f32_16x16x32_bf16 v[100:103], v[144:147], v[184:187], v[100:103]
	v_mfma_f32_16x16x32_bf16 v[96:99], v[152:155], v[184:187], v[96:99]
	v_mfma_f32_16x16x32_bf16 v[84:87], v[144:147], v[198:201], v[84:87]
	v_mfma_f32_16x16x32_bf16 v[80:83], v[152:155], v[198:201], v[80:83]
	v_mfma_f32_16x16x32_bf16 v[68:71], v[144:147], v[206:209], v[68:71]
	v_mfma_f32_16x16x32_bf16 v[64:67], v[152:155], v[206:209], v[64:67]
	v_mfma_f32_16x16x32_bf16 v[116:119], v[148:151], v[164:167], v[116:119]
	v_mfma_f32_16x16x32_bf16 v[112:115], v[156:159], v[164:167], v[112:115]
	v_mfma_f32_16x16x32_bf16 v[100:103], v[148:151], v[188:191], v[100:103]
	v_mfma_f32_16x16x32_bf16 v[96:99], v[156:159], v[188:191], v[96:99]
	v_mfma_f32_16x16x32_bf16 v[84:87], v[148:151], v[202:205], v[84:87]
	v_mfma_f32_16x16x32_bf16 v[80:83], v[156:159], v[202:205], v[80:83]
	v_mfma_f32_16x16x32_bf16 v[68:71], v[148:151], v[210:213], v[68:71]
	v_mfma_f32_16x16x32_bf16 v[64:67], v[156:159], v[210:213], v[64:67]
	s_setprio 0
	s_barrier
	s_add_i32 s40, s60, s15
	v_lshl_add_u64 v[214:215], v[214:215], 0, s[28:29]
	s_mov_b32 m0, s40
	ds_read_b128 v[160:163], v197 offset:49152
	ds_read_b128 v[164:167], v197 offset:50176
	ds_read_b128 v[184:187], v197 offset:51200
	ds_read_b128 v[188:191], v197 offset:52224
	ds_read_b128 v[198:201], v197 offset:53248
	ds_read_b128 v[202:205], v197 offset:54272
	ds_read_b128 v[206:209], v197 offset:55296
	ds_read_b128 v[210:213], v197 offset:56320
	global_load_lds_dwordx4 v[214:215], off
	v_lshl_add_u64 v[214:215], v[216:217], 0, s[28:29]
	s_add_i32 m0, s40, 0x2000
	s_add_i32 s40, s61, s15
	global_load_lds_dwordx4 v[214:215], off
	v_lshl_add_u64 v[214:215], v[218:219], 0, s[28:29]
	s_mov_b32 m0, s40
	s_nop 0
	global_load_lds_dwordx4 v[214:215], off
	v_lshl_add_u64 v[214:215], v[220:221], 0, s[28:29]
	s_add_i32 m0, s40, 0x2000
	s_nop 0
	global_load_lds_dwordx4 v[214:215], off
	s_waitcnt vmcnt(6)
	s_waitcnt lgkmcnt(0)
	s_barrier
	s_setprio 1
	s_waitcnt lgkmcnt(0)
	v_mfma_f32_16x16x32_bf16 v[60:63], v[128:131], v[160:163], v[60:63]
	v_mfma_f32_16x16x32_bf16 v[56:59], v[136:139], v[160:163], v[56:59]
	v_mfma_f32_16x16x32_bf16 v[44:47], v[128:131], v[184:187], v[44:47]
	v_mfma_f32_16x16x32_bf16 v[40:43], v[136:139], v[184:187], v[40:43]
	v_lshl_add_u64 v[214:215], v[222:223], 0, s[28:29]
	s_mov_b32 m0, s47
	s_nop 0
	global_load_lds_dwordx4 v[214:215], off
	v_mfma_f32_16x16x32_bf16 v[28:31], v[128:131], v[198:201], v[28:31]
	v_mfma_f32_16x16x32_bf16 v[24:27], v[136:139], v[198:201], v[24:27]
	v_mfma_f32_16x16x32_bf16 v[12:15], v[128:131], v[206:209], v[12:15]
	v_mfma_f32_16x16x32_bf16 v[8:11], v[136:139], v[206:209], v[8:11]
	v_mfma_f32_16x16x32_bf16 v[60:63], v[132:135], v[164:167], v[60:63]
	v_mfma_f32_16x16x32_bf16 v[56:59], v[140:143], v[164:167], v[56:59]
	v_mfma_f32_16x16x32_bf16 v[44:47], v[132:135], v[188:191], v[44:47]
	v_mfma_f32_16x16x32_bf16 v[40:43], v[140:143], v[188:191], v[40:43]
	v_lshl_add_u64 v[214:215], v[224:225], 0, s[28:29]
	s_mov_b32 m0, s48
	s_nop 0
	global_load_lds_dwordx4 v[214:215], off
	v_mfma_f32_16x16x32_bf16 v[28:31], v[132:135], v[202:205], v[28:31]
	v_mfma_f32_16x16x32_bf16 v[24:27], v[140:143], v[202:205], v[24:27]
	v_mfma_f32_16x16x32_bf16 v[12:15], v[132:135], v[210:213], v[12:15]
	v_mfma_f32_16x16x32_bf16 v[8:11], v[140:143], v[210:213], v[8:11]
	s_setprio 0
	s_setprio 1
	v_mfma_f32_16x16x32_bf16 v[52:55], v[144:147], v[160:163], v[52:55]
	v_mfma_f32_16x16x32_bf16 v[48:51], v[152:155], v[160:163], v[48:51]
	v_mfma_f32_16x16x32_bf16 v[36:39], v[144:147], v[184:187], v[36:39]
	v_mfma_f32_16x16x32_bf16 v[32:35], v[152:155], v[184:187], v[32:35]
	v_mfma_f32_16x16x32_bf16 v[20:23], v[144:147], v[198:201], v[20:23]
	v_mfma_f32_16x16x32_bf16 v[16:19], v[152:155], v[198:201], v[16:19]
	v_mfma_f32_16x16x32_bf16 v[4:7], v[144:147], v[206:209], v[4:7]
	v_mfma_f32_16x16x32_bf16 v[0:3], v[152:155], v[206:209], v[0:3]
	v_mfma_f32_16x16x32_bf16 v[52:55], v[148:151], v[164:167], v[52:55]
	v_mfma_f32_16x16x32_bf16 v[48:51], v[156:159], v[164:167], v[48:51]
	v_mfma_f32_16x16x32_bf16 v[36:39], v[148:151], v[188:191], v[36:39]
	v_mfma_f32_16x16x32_bf16 v[32:35], v[156:159], v[188:191], v[32:35]
	v_mfma_f32_16x16x32_bf16 v[20:23], v[148:151], v[202:205], v[20:23]
	v_mfma_f32_16x16x32_bf16 v[16:19], v[156:159], v[202:205], v[16:19]
	v_mfma_f32_16x16x32_bf16 v[4:7], v[148:151], v[210:213], v[4:7]
	v_mfma_f32_16x16x32_bf16 v[0:3], v[156:159], v[210:213], v[0:3]
	s_setprio 0
	s_barrier
	s_add_u32 s38, s38, 0x100
	s_addc_u32 s39, s39, 0
	s_add_u32 s57, s57, 0x100
	s_addc_u32 s58, s58, 0
	s_cmp_ge_i32 s59, s49
	s_mov_b32 s40, s59
	s_cbranch_scc0 .LBB0_1086
